# UP epilogue VALU stream re-packed between memory/control instructions (independent taps fill DPP/trans wait states instead of s_nop), sigmoid mul/add packed, (rs,rs) movs folded
# speedup vs baseline: 1.0043x; 1.0043x over previous
.LBB0_563:
	s_or_b64 exec, exec, s[48:49]
	s_waitcnt lgkmcnt(0)
	s_barrier
	ds_read_b128 v[150:153], v223 offset:512
	ds_read_b128 v[154:157], v223 offset:1536
	ds_read_b128 v[162:165], v223 offset:2560
	ds_read_b128 v[138:141], v223 offset:3584
	v_mov_b32_e32 v158, 0
	v_mov_b32_e32 v159, 0
	v_mov_b32_e32 v160, 0
	v_mov_b32_e32 v161, 0
	s_and_saveexec_b64 s[48:49], s[30:31]
	v_add_u32_e32 v1, s91, v215
	ds_read_b128 v[158:161], v1 offset:512
	s_or_b64 exec, exec, s[48:49]
	v_lshl_add_u32 v1, s28, 1, v173
	v_mad_i64_i32 v[206:207], s[48:49], v1, s76, 0
	v_fmamk_f32 v1, v149, 0x3a800000, v222
	v_rsq_f32_e32 v196, v1
	v_fmamk_f32 v1, v146, 0x3a800000, v222
	v_rsq_f32_e32 v198, v1
	s_waitcnt lgkmcnt(0)
	v_fma_f32 v146, v166, v162, v138
	s_nop 4
	v_fmac_f32_dpp v146, v166, v154 row_shr:1 row_mask:0xf bank_mask:0xf
	v_fmamk_f32 v147, v148, 0x3a800000, v222
	v_fmac_f32_dpp v146, v166, v150 row_shr:2 row_mask:0xf bank_mask:0xf
	v_rsq_f32_e32 v194, v147
	v_pk_fma_f32 v[78:79], v[78:79], v[198:199], v[122:123] op_sel_hi:[1,0,1]
	v_fma_f32 v147, v167, v163, v139
	v_pk_fma_f32 v[148:149], v[168:169], v[164:165], v[140:141]
	v_fmac_f32_dpp v146, v78, v154 row_shl:15 row_mask:0xf bank_mask:0xf
	v_fmac_f32_dpp v147, v167, v155 row_shr:1 row_mask:0xf bank_mask:0xf
	v_fmac_f32_dpp v146, v78, v150 row_shl:14 row_mask:0xf bank_mask:0xf
	v_pk_fma_f32 v[80:81], v[80:81], v[198:199], v[124:125] op_sel_hi:[1,0,1]
	v_fmac_f32_dpp v147, v167, v151 row_shr:2 row_mask:0xf bank_mask:0xf
	v_pk_fma_f32 v[224:225], v[130:131], v[196:197], v[122:123] op_sel_hi:[1,0,1]
	v_fmac_f32_dpp v147, v79, v155 row_shl:15 row_mask:0xf bank_mask:0xf
	v_fmac_f32_dpp v148, v168, v156 row_shr:1 row_mask:0xf bank_mask:0xf
	v_fmac_f32_dpp v147, v79, v151 row_shl:14 row_mask:0xf bank_mask:0xf
	v_pk_fma_f32 v[130:131], v[78:79], v[162:163], v[138:139]
	v_fmac_f32_dpp v148, v168, v152 row_shr:2 row_mask:0xf bank_mask:0xf
	v_pk_fma_f32 v[208:209], v[132:133], v[196:197], v[124:125] op_sel_hi:[1,0,1]
	v_fmac_f32_dpp v148, v80, v156 row_shl:15 row_mask:0xf bank_mask:0xf
	v_fmac_f32_dpp v149, v169, v157 row_shr:1 row_mask:0xf bank_mask:0xf
	v_fmac_f32_dpp v148, v80, v152 row_shl:14 row_mask:0xf bank_mask:0xf
	v_pk_fma_f32 v[132:133], v[80:81], v[164:165], v[140:141]
	v_fmac_f32_dpp v149, v169, v153 row_shr:2 row_mask:0xf bank_mask:0xf
	v_pk_fma_f32 v[134:135], v[134:135], v[194:195], v[122:123] op_sel_hi:[1,0,1]
	v_fmac_f32_dpp v149, v81, v157 row_shl:15 row_mask:0xf bank_mask:0xf
	v_pk_fma_f32 v[136:137], v[136:137], v[194:195], v[124:125] op_sel_hi:[1,0,1]
	v_fmac_f32_dpp v149, v81, v153 row_shl:14 row_mask:0xf bank_mask:0xf
	v_fmac_f32_dpp v130, v78, v154 row_shr:1 row_mask:0xf bank_mask:0xf
	s_lshl_b32 s46, s46, 7
	v_fmac_f32_dpp v130, v78, v150 row_shr:2 row_mask:0xf bank_mask:0xf
	v_fma_f32 v78, v224, v162, v138
	v_fmac_f32_dpp v130, v224, v154 row_shl:15 row_mask:0xf bank_mask:0xf
	v_fmac_f32_dpp v131, v79, v155 row_shr:1 row_mask:0xf bank_mask:0xf
	v_fmac_f32_dpp v130, v224, v150 row_shl:14 row_mask:0xf bank_mask:0xf
	v_or_b32_e32 v200, s46, v184
	v_fmac_f32_dpp v131, v79, v151 row_shr:2 row_mask:0xf bank_mask:0xf
	v_fma_f32 v79, v225, v163, v139
	v_fmac_f32_dpp v131, v225, v155 row_shl:15 row_mask:0xf bank_mask:0xf
	v_pk_fma_f32 v[138:139], v[134:135], v[162:163], v[138:139]
	v_fmac_f32_dpp v131, v225, v151 row_shl:14 row_mask:0xf bank_mask:0xf
	v_fmac_f32_dpp v132, v80, v156 row_shr:1 row_mask:0xf bank_mask:0xf
	v_ashrrev_i32_e32 v201, 31, v200
	v_fmac_f32_dpp v132, v80, v152 row_shr:2 row_mask:0xf bank_mask:0xf
	v_fma_f32 v80, v208, v164, v140
	v_fmac_f32_dpp v132, v208, v156 row_shl:15 row_mask:0xf bank_mask:0xf
	v_fmac_f32_dpp v133, v81, v157 row_shr:1 row_mask:0xf bank_mask:0xf
	v_fmac_f32_dpp v132, v208, v152 row_shl:14 row_mask:0xf bank_mask:0xf
	v_lshl_add_u64 v[168:169], s[24:25], 0, v[206:207]
	v_fmac_f32_dpp v133, v81, v153 row_shr:2 row_mask:0xf bank_mask:0xf
	v_fma_f32 v81, v209, v165, v141
	v_fmac_f32_dpp v133, v209, v157 row_shl:15 row_mask:0xf bank_mask:0xf
	v_pk_fma_f32 v[140:141], v[136:137], v[164:165], v[140:141]
	v_fmac_f32_dpp v133, v209, v153 row_shl:14 row_mask:0xf bank_mask:0xf
	v_lshl_add_u64 v[166:167], v[200:201], 2, v[168:169]
	v_fmac_f32_dpp v78, v224, v154 row_shr:1 row_mask:0xf bank_mask:0xf
	v_fmac_f32_dpp v79, v225, v155 row_shr:1 row_mask:0xf bank_mask:0xf
	v_fmac_f32_dpp v78, v224, v150 row_shr:2 row_mask:0xf bank_mask:0xf
	v_fmac_f32_dpp v79, v225, v151 row_shr:2 row_mask:0xf bank_mask:0xf
	v_fmac_f32_dpp v78, v134, v154 row_shl:15 row_mask:0xf bank_mask:0xf
	v_fmac_f32_dpp v79, v135, v155 row_shl:15 row_mask:0xf bank_mask:0xf
	v_fmac_f32_dpp v78, v134, v150 row_shl:14 row_mask:0xf bank_mask:0xf
	v_fmac_f32_dpp v79, v135, v151 row_shl:14 row_mask:0xf bank_mask:0xf
	v_fmac_f32_dpp v80, v208, v156 row_shr:1 row_mask:0xf bank_mask:0xf
	v_fmac_f32_dpp v81, v209, v157 row_shr:1 row_mask:0xf bank_mask:0xf
	v_fmac_f32_dpp v80, v208, v152 row_shr:2 row_mask:0xf bank_mask:0xf
	v_fmac_f32_dpp v81, v209, v153 row_shr:2 row_mask:0xf bank_mask:0xf
	v_fmac_f32_dpp v80, v136, v156 row_shl:15 row_mask:0xf bank_mask:0xf
	v_fmac_f32_dpp v81, v137, v157 row_shl:15 row_mask:0xf bank_mask:0xf
	v_fmac_f32_dpp v80, v136, v152 row_shl:14 row_mask:0xf bank_mask:0xf
	v_fmac_f32_dpp v81, v137, v153 row_shl:14 row_mask:0xf bank_mask:0xf
	v_fmac_f32_dpp v138, v134, v154 row_shr:1 row_mask:0xf bank_mask:0xf
	v_fmac_f32_dpp v139, v135, v155 row_shr:1 row_mask:0xf bank_mask:0xf
	v_fmac_f32_dpp v138, v134, v150 row_shr:2 row_mask:0xf bank_mask:0xf
	v_fmac_f32_dpp v139, v135, v151 row_shr:2 row_mask:0xf bank_mask:0xf
	v_fmac_f32_dpp v138, v158, v154 row_shl:15 row_mask:0xf bank_mask:0xf
	v_fmac_f32_dpp v139, v159, v155 row_shl:15 row_mask:0xf bank_mask:0xf
	v_fmac_f32_dpp v138, v158, v150 row_shl:14 row_mask:0xf bank_mask:0xf
	v_fmac_f32_dpp v139, v159, v151 row_shl:14 row_mask:0xf bank_mask:0xf
	v_fmac_f32_dpp v140, v136, v156 row_shr:1 row_mask:0xf bank_mask:0xf
	v_fmac_f32_dpp v141, v137, v157 row_shr:1 row_mask:0xf bank_mask:0xf
	v_fmac_f32_dpp v140, v136, v152 row_shr:2 row_mask:0xf bank_mask:0xf
	v_fmac_f32_dpp v141, v137, v153 row_shr:2 row_mask:0xf bank_mask:0xf
	v_fmac_f32_dpp v140, v160, v156 row_shl:15 row_mask:0xf bank_mask:0xf
	v_fmac_f32_dpp v141, v161, v157 row_shl:15 row_mask:0xf bank_mask:0xf
	v_fmac_f32_dpp v140, v160, v152 row_shl:14 row_mask:0xf bank_mask:0xf
	v_fmac_f32_dpp v141, v161, v153 row_shl:14 row_mask:0xf bank_mask:0xf
	s_and_saveexec_b64 s[48:49], s[34:35]
	s_cbranch_execz .LBB0_567
	v_add_co_u32_e32 v134, vcc, 0x2000, v166
	s_nop 1
	v_addc_co_u32_e32 v135, vcc, 0, v167, vcc
	global_store_dwordx4 v[134:135], v[138:141], off offset:3072
.LBB0_567:
	s_or_b64 exec, exec, s[48:49]
	ds_read_b128 v[150:153], v223
	ds_read_b128 v[154:157], v223 offset:1024
	ds_read_b128 v[162:165], v223 offset:2048
	ds_read_b128 v[134:137], v223 offset:3072
	v_mov_b32_e32 v158, 0
	v_mov_b32_e32 v159, 0
	v_mov_b32_e32 v160, 0
	v_mov_b32_e32 v161, 0
	s_and_saveexec_b64 s[48:49], s[30:31]
	v_add_u32_e32 v1, 0, v215
	v_add_u32_e32 v1, 0x20000, v1
	ds_read_b128 v[158:161], v1
	s_or_b64 exec, exec, s[48:49]
	v_mov_b32_e32 v195, v194
	v_mov_b32_e32 v199, v198
	v_pk_fma_f32 v[208:209], v[62:63], v[194:195], v[118:119] op_sel_hi:[1,0,1]
	v_pk_fma_f32 v[62:63], v[52:53], v[196:197], v[120:121] op_sel_hi:[1,0,1]
	v_pk_fma_f32 v[52:53], v[46:47], v[198:199], v[118:119] op_sel_hi:[1,0,1]
	s_waitcnt lgkmcnt(0)
	v_pk_fma_f32 v[46:47], v[142:143], v[162:163], v[134:135]
	s_nop 4
	v_fmac_f32_dpp v46, v142, v154 row_shr:1 row_mask:0xf bank_mask:0xf
	v_mov_b32_e32 v197, v196
	v_fmac_f32_dpp v46, v142, v150 row_shr:2 row_mask:0xf bank_mask:0xf
	v_fmac_f32_dpp v47, v143, v155 row_shr:1 row_mask:0xf bank_mask:0xf
	v_fmac_f32_dpp v46, v52, v154 row_shl:15 row_mask:0xf bank_mask:0xf
	v_pk_fma_f32 v[206:207], v[64:65], v[194:195], v[120:121] op_sel_hi:[1,0,1]
	v_fmac_f32_dpp v46, v52, v150 row_shl:14 row_mask:0xf bank_mask:0xf
	v_pk_fma_f32 v[64:65], v[50:51], v[196:197], v[118:119] op_sel_hi:[1,0,1]
	v_fmac_f32_dpp v47, v143, v151 row_shr:2 row_mask:0xf bank_mask:0xf
	v_pk_fma_f32 v[50:51], v[48:49], v[198:199], v[120:121] op_sel_hi:[1,0,1]
	v_fmac_f32_dpp v47, v53, v155 row_shl:15 row_mask:0xf bank_mask:0xf
	v_pk_fma_f32 v[48:49], v[144:145], v[164:165], v[136:137]
	v_fmac_f32_dpp v47, v53, v151 row_shl:14 row_mask:0xf bank_mask:0xf
	v_fmac_f32_dpp v48, v144, v156 row_shr:1 row_mask:0xf bank_mask:0xf
	v_fmac_f32_dpp v49, v145, v157 row_shr:1 row_mask:0xf bank_mask:0xf
	v_fmac_f32_dpp v48, v144, v152 row_shr:2 row_mask:0xf bank_mask:0xf
	v_fmac_f32_dpp v49, v145, v153 row_shr:2 row_mask:0xf bank_mask:0xf
	v_fmac_f32_dpp v48, v50, v156 row_shl:15 row_mask:0xf bank_mask:0xf
	v_fmac_f32_dpp v49, v51, v157 row_shl:15 row_mask:0xf bank_mask:0xf
	v_fmac_f32_dpp v48, v50, v152 row_shl:14 row_mask:0xf bank_mask:0xf
	v_fmac_f32_dpp v49, v51, v153 row_shl:14 row_mask:0xf bank_mask:0xf
	v_pk_mul_f32 v[244:245], v[48:49], s[100:101]
	v_exp_f32_e32 v244, v244
	v_exp_f32_e32 v245, v245
	v_pk_mul_f32 v[48:49], v[148:149], v[48:49]
	v_pk_add_f32 v[244:245], v[244:245], s[98:99]
	v_rcp_f32_e32 v144, v244
	v_rcp_f32_e32 v145, v245
	v_pk_mul_f32 v[244:245], v[46:47], s[100:101]
	v_exp_f32_e32 v244, v244
	v_exp_f32_e32 v245, v245
	v_pk_mul_f32 v[46:47], v[146:147], v[46:47]
	v_pk_add_f32 v[244:245], v[244:245], s[98:99]
	v_rcp_f32_e32 v142, v244
	v_rcp_f32_e32 v143, v245
	v_pk_mul_f32 v[48:49], v[48:49], v[144:145]
	v_pk_mul_f32 v[46:47], v[46:47], v[142:143]
	v_pk_fma_f32 v[142:143], v[52:53], v[162:163], v[134:135]
	s_nop 0
	v_fmac_f32_dpp v142, v52, v154 row_shr:1 row_mask:0xf bank_mask:0xf
	v_fmac_f32_dpp v143, v53, v155 row_shr:1 row_mask:0xf bank_mask:0xf
	v_fmac_f32_dpp v142, v52, v150 row_shr:2 row_mask:0xf bank_mask:0xf
	v_fma_f32 v52, v50, v164, v136
	v_fmac_f32_dpp v142, v64, v154 row_shl:15 row_mask:0xf bank_mask:0xf
	v_fmac_f32_dpp v143, v53, v151 row_shr:2 row_mask:0xf bank_mask:0xf
	v_fmac_f32_dpp v142, v64, v150 row_shl:14 row_mask:0xf bank_mask:0xf
	v_fmac_f32_dpp v143, v65, v155 row_shl:15 row_mask:0xf bank_mask:0xf
	v_fmac_f32_dpp v52, v50, v156 row_shr:1 row_mask:0xf bank_mask:0xf
	v_fmac_f32_dpp v143, v65, v151 row_shl:14 row_mask:0xf bank_mask:0xf
	v_fma_f32 v53, v51, v165, v137
	v_fmac_f32_dpp v52, v50, v152 row_shr:2 row_mask:0xf bank_mask:0xf
	v_fmac_f32_dpp v53, v51, v157 row_shr:1 row_mask:0xf bank_mask:0xf
	v_fmac_f32_dpp v52, v62, v156 row_shl:15 row_mask:0xf bank_mask:0xf
	v_fmac_f32_dpp v53, v51, v153 row_shr:2 row_mask:0xf bank_mask:0xf
	v_fmac_f32_dpp v52, v62, v152 row_shl:14 row_mask:0xf bank_mask:0xf
	v_fmac_f32_dpp v53, v63, v157 row_shl:15 row_mask:0xf bank_mask:0xf
	v_pk_mul_f32 v[130:131], v[130:131], v[142:143]
	v_fmac_f32_dpp v53, v63, v153 row_shl:14 row_mask:0xf bank_mask:0xf
	v_pk_mul_f32 v[244:245], v[52:53], s[100:101]
	v_exp_f32_e32 v244, v244
	v_exp_f32_e32 v245, v245
	v_pk_mul_f32 v[52:53], v[132:133], v[52:53]
	v_pk_add_f32 v[244:245], v[244:245], s[98:99]
	v_rcp_f32_e32 v144, v244
	v_rcp_f32_e32 v145, v245
	v_pk_mul_f32 v[244:245], v[142:143], s[100:101]
	v_exp_f32_e32 v244, v244
	v_exp_f32_e32 v245, v245
	v_pk_mul_f32 v[52:53], v[52:53], v[144:145]
	v_pk_add_f32 v[244:245], v[244:245], s[98:99]
	v_rcp_f32_e32 v50, v244
	v_rcp_f32_e32 v51, v245
	s_nop 0
	v_pk_mul_f32 v[50:51], v[130:131], v[50:51]
	v_pk_fma_f32 v[130:131], v[64:65], v[162:163], v[134:135]
	v_pk_fma_f32 v[134:135], v[208:209], v[162:163], v[134:135]
	v_fmac_f32_dpp v130, v64, v154 row_shr:1 row_mask:0xf bank_mask:0xf
	v_fmac_f32_dpp v131, v65, v155 row_shr:1 row_mask:0xf bank_mask:0xf
	v_fmac_f32_dpp v130, v64, v150 row_shr:2 row_mask:0xf bank_mask:0xf
	v_fma_f32 v64, v62, v164, v136
	v_fmac_f32_dpp v130, v208, v154 row_shl:15 row_mask:0xf bank_mask:0xf
	v_fmac_f32_dpp v131, v65, v151 row_shr:2 row_mask:0xf bank_mask:0xf
	v_fmac_f32_dpp v130, v208, v150 row_shl:14 row_mask:0xf bank_mask:0xf
	v_mul_f32_e32 v1, 0xbfb8aa3b, v130
	v_fmac_f32_dpp v131, v209, v155 row_shl:15 row_mask:0xf bank_mask:0xf
	v_exp_f32_e32 v1, v1
	v_fmac_f32_dpp v131, v209, v151 row_shl:14 row_mask:0xf bank_mask:0xf
	v_fmac_f32_dpp v64, v62, v156 row_shr:1 row_mask:0xf bank_mask:0xf
	v_fma_f32 v65, v63, v165, v137
	v_fmac_f32_dpp v64, v62, v152 row_shr:2 row_mask:0xf bank_mask:0xf
	v_add_f32_e32 v1, 1.0, v1
	v_fmac_f32_dpp v64, v206, v156 row_shl:15 row_mask:0xf bank_mask:0xf
	v_rcp_f32_e32 v62, v1
	v_fmac_f32_dpp v64, v206, v152 row_shl:14 row_mask:0xf bank_mask:0xf
	v_fmac_f32_dpp v65, v63, v157 row_shr:1 row_mask:0xf bank_mask:0xf
	v_mul_f32_e32 v1, 0xbfb8aa3b, v131
	v_fmac_f32_dpp v65, v63, v153 row_shr:2 row_mask:0xf bank_mask:0xf
	v_exp_f32_e32 v1, v1
	v_fmac_f32_dpp v65, v207, v157 row_shl:15 row_mask:0xf bank_mask:0xf
	v_add_f32_e32 v1, 1.0, v1
	v_fmac_f32_dpp v65, v207, v153 row_shl:14 row_mask:0xf bank_mask:0xf
	v_pk_mul_f32 v[244:245], v[64:65], s[100:101]
	v_exp_f32_e32 v244, v244
	v_exp_f32_e32 v245, v245
	v_rcp_f32_e32 v63, v1
	v_pk_add_f32 v[244:245], v[244:245], s[98:99]
	v_rcp_f32_e32 v132, v244
	v_rcp_f32_e32 v133, v245
	v_pk_mul_f32 v[64:65], v[80:81], v[64:65]
	v_pk_mul_f32 v[78:79], v[78:79], v[130:131]
	v_pk_mul_f32 v[64:65], v[64:65], v[132:133]
	v_pk_mul_f32 v[62:63], v[78:79], v[62:63]
	v_pk_fma_f32 v[136:137], v[206:207], v[164:165], v[136:137]
	v_fmac_f32_dpp v134, v208, v154 row_shr:1 row_mask:0xf bank_mask:0xf
	v_fmac_f32_dpp v135, v209, v155 row_shr:1 row_mask:0xf bank_mask:0xf
	v_fmac_f32_dpp v134, v208, v150 row_shr:2 row_mask:0xf bank_mask:0xf
	v_fmac_f32_dpp v135, v209, v151 row_shr:2 row_mask:0xf bank_mask:0xf
	v_fmac_f32_dpp v134, v158, v154 row_shl:15 row_mask:0xf bank_mask:0xf
	v_fmac_f32_dpp v135, v159, v155 row_shl:15 row_mask:0xf bank_mask:0xf
	v_fmac_f32_dpp v134, v158, v150 row_shl:14 row_mask:0xf bank_mask:0xf
	v_fmac_f32_dpp v135, v159, v151 row_shl:14 row_mask:0xf bank_mask:0xf
	v_fmac_f32_dpp v136, v206, v156 row_shr:1 row_mask:0xf bank_mask:0xf
	v_fmac_f32_dpp v137, v207, v157 row_shr:1 row_mask:0xf bank_mask:0xf
	v_fmac_f32_dpp v136, v206, v152 row_shr:2 row_mask:0xf bank_mask:0xf
	v_fmac_f32_dpp v137, v207, v153 row_shr:2 row_mask:0xf bank_mask:0xf
	v_fmac_f32_dpp v136, v160, v156 row_shl:15 row_mask:0xf bank_mask:0xf
	v_fmac_f32_dpp v137, v161, v157 row_shl:15 row_mask:0xf bank_mask:0xf
	v_fmac_f32_dpp v136, v160, v152 row_shl:14 row_mask:0xf bank_mask:0xf
	v_fmac_f32_dpp v137, v161, v153 row_shl:14 row_mask:0xf bank_mask:0xf
	s_and_saveexec_b64 s[48:49], s[34:35]
	s_cbranch_execz .LBB0_571
	global_store_dwordx4 v[166:167], v[134:137], off
.LBB0_571:
	s_or_b64 exec, exec, s[48:49]
	v_mul_f32_e32 v79, 0xbfb8aa3b, v136
	v_exp_f32_e32 v1, v79
	v_mul_f32_e32 v79, 0xbfb8aa3b, v137
	v_exp_f32_e32 v79, v79
	v_add_f32_e32 v1, 1.0, v1
	v_rcp_f32_e32 v80, v1
	v_add_f32_e32 v1, 1.0, v79
	v_rcp_f32_e32 v81, v1
	v_pk_mul_f32 v[244:245], v[134:135], s[100:101]
	v_exp_f32_e32 v244, v244
	v_exp_f32_e32 v245, v245
	v_pk_mul_f32 v[130:131], v[140:141], v[136:137]
	v_pk_add_f32 v[244:245], v[244:245], s[98:99]
	v_rcp_f32_e32 v78, v244
	v_rcp_f32_e32 v79, v245
	v_pk_mul_f32 v[132:133], v[138:139], v[134:135]
	v_pk_mul_f32 v[80:81], v[130:131], v[80:81]
	v_pk_mul_f32 v[78:79], v[132:133], v[78:79]
	v_mov_b32_e32 v134, 0
	ds_read_b128 v[142:145], v223 offset:512
	ds_read_b128 v[146:149], v223 offset:1536
	ds_read_b128 v[154:157], v223 offset:2560
	ds_read_b128 v[130:133], v223 offset:3584
	v_mov_b32_e32 v150, 0
	v_mov_b32_e32 v151, 0
	v_mov_b32_e32 v152, 0
	v_mov_b32_e32 v153, 0
	s_and_saveexec_b64 s[48:49], s[0:1]
	v_add_u32_e32 v1, s91, v216
	ds_read_b128 v[150:153], v1 offset:512
	s_or_b64 exec, exec, s[48:49]
	v_fmamk_f32 v135, v202, 0x3a800000, v222
	v_rsq_f32_e32 v160, v135
	s_waitcnt lgkmcnt(0)
	v_pk_fma_f32 v[138:139], v[126:127], v[154:155], v[130:131]
	s_nop 4
	v_fmac_f32_dpp v138, v126, v146 row_shr:1 row_mask:0xf bank_mask:0xf
	v_pk_fma_f32 v[102:103], v[102:103], v[160:161], v[122:123] op_sel_hi:[1,0,1]
	v_fmac_f32_dpp v138, v126, v142 row_shr:2 row_mask:0xf bank_mask:0xf
	v_pk_fma_f32 v[140:141], v[128:129], v[156:157], v[132:133]
	v_fmac_f32_dpp v138, v102, v146 row_shl:15 row_mask:0xf bank_mask:0xf
	v_fmac_f32_dpp v139, v127, v147 row_shr:1 row_mask:0xf bank_mask:0xf
	v_fmac_f32_dpp v138, v102, v142 row_shl:14 row_mask:0xf bank_mask:0xf
	v_fmamk_f32 v1, v204, 0x3a800000, v222
	v_fmac_f32_dpp v139, v127, v143 row_shr:2 row_mask:0xf bank_mask:0xf
	v_rsq_f32_e32 v158, v1
	v_fmac_f32_dpp v139, v103, v147 row_shl:15 row_mask:0xf bank_mask:0xf
	v_fmamk_f32 v1, v205, 0x3a800000, v222
	v_fmac_f32_dpp v139, v103, v143 row_shl:14 row_mask:0xf bank_mask:0xf
	v_fmac_f32_dpp v140, v128, v148 row_shr:1 row_mask:0xf bank_mask:0xf
	v_rsq_f32_e32 v162, v1
	v_fmac_f32_dpp v140, v128, v144 row_shr:2 row_mask:0xf bank_mask:0xf
	v_pk_fma_f32 v[104:105], v[104:105], v[160:161], v[124:125] op_sel_hi:[1,0,1]
	v_pk_fma_f32 v[164:165], v[106:107], v[162:163], v[122:123] op_sel_hi:[1,0,1]
	v_fmac_f32_dpp v141, v129, v149 row_shr:1 row_mask:0xf bank_mask:0xf
	v_fmac_f32_dpp v140, v104, v148 row_shl:15 row_mask:0xf bank_mask:0xf
	v_pk_fma_f32 v[106:107], v[102:103], v[154:155], v[130:131]
	v_fmac_f32_dpp v140, v104, v144 row_shl:14 row_mask:0xf bank_mask:0xf
	v_fmac_f32_dpp v141, v129, v145 row_shr:2 row_mask:0xf bank_mask:0xf
	v_pk_fma_f32 v[136:137], v[108:109], v[162:163], v[124:125] op_sel_hi:[1,0,1]
	v_fmac_f32_dpp v141, v105, v149 row_shl:15 row_mask:0xf bank_mask:0xf
	v_pk_fma_f32 v[108:109], v[104:105], v[156:157], v[132:133]
	v_fmac_f32_dpp v141, v105, v145 row_shl:14 row_mask:0xf bank_mask:0xf
	v_fmac_f32_dpp v106, v102, v146 row_shr:1 row_mask:0xf bank_mask:0xf
	v_pk_fma_f32 v[110:111], v[110:111], v[158:159], v[122:123] op_sel_hi:[1,0,1]
	v_fmac_f32_dpp v106, v102, v142 row_shr:2 row_mask:0xf bank_mask:0xf
	v_fmac_f32_dpp v107, v103, v147 row_shr:1 row_mask:0xf bank_mask:0xf
	v_fmac_f32_dpp v106, v164, v146 row_shl:15 row_mask:0xf bank_mask:0xf
	v_pk_fma_f32 v[112:113], v[112:113], v[158:159], v[124:125] op_sel_hi:[1,0,1]
	v_fmac_f32_dpp v106, v164, v142 row_shl:14 row_mask:0xf bank_mask:0xf
	v_fmac_f32_dpp v107, v103, v143 row_shr:2 row_mask:0xf bank_mask:0xf
	v_pk_fma_f32 v[102:103], v[164:165], v[154:155], v[130:131]
	v_fmac_f32_dpp v107, v165, v147 row_shl:15 row_mask:0xf bank_mask:0xf
	v_pk_fma_f32 v[130:131], v[110:111], v[154:155], v[130:131]
	v_fmac_f32_dpp v107, v165, v143 row_shl:14 row_mask:0xf bank_mask:0xf
	v_fmac_f32_dpp v108, v104, v148 row_shr:1 row_mask:0xf bank_mask:0xf
	v_fmac_f32_dpp v109, v105, v149 row_shr:1 row_mask:0xf bank_mask:0xf
	v_fmac_f32_dpp v108, v104, v144 row_shr:2 row_mask:0xf bank_mask:0xf
	v_fma_f32 v104, v136, v156, v132
	v_fmac_f32_dpp v108, v136, v148 row_shl:15 row_mask:0xf bank_mask:0xf
	v_mov_b32_e32 v135, 0
	v_fmac_f32_dpp v108, v136, v144 row_shl:14 row_mask:0xf bank_mask:0xf
	v_fmac_f32_dpp v109, v105, v145 row_shr:2 row_mask:0xf bank_mask:0xf
	v_fma_f32 v105, v137, v157, v133
	v_fmac_f32_dpp v109, v137, v149 row_shl:15 row_mask:0xf bank_mask:0xf
	v_pk_fma_f32 v[132:133], v[112:113], v[156:157], v[132:133]
	v_fmac_f32_dpp v109, v137, v145 row_shl:14 row_mask:0xf bank_mask:0xf
	v_fmac_f32_dpp v102, v164, v146 row_shr:1 row_mask:0xf bank_mask:0xf
	v_fmac_f32_dpp v103, v165, v147 row_shr:1 row_mask:0xf bank_mask:0xf
	v_fmac_f32_dpp v102, v164, v142 row_shr:2 row_mask:0xf bank_mask:0xf
	v_fmac_f32_dpp v103, v165, v143 row_shr:2 row_mask:0xf bank_mask:0xf
	v_fmac_f32_dpp v102, v110, v146 row_shl:15 row_mask:0xf bank_mask:0xf
	v_fmac_f32_dpp v103, v111, v147 row_shl:15 row_mask:0xf bank_mask:0xf
	v_fmac_f32_dpp v102, v110, v142 row_shl:14 row_mask:0xf bank_mask:0xf
	v_fmac_f32_dpp v103, v111, v143 row_shl:14 row_mask:0xf bank_mask:0xf
	v_fmac_f32_dpp v104, v136, v148 row_shr:1 row_mask:0xf bank_mask:0xf
	v_fmac_f32_dpp v105, v137, v149 row_shr:1 row_mask:0xf bank_mask:0xf
	v_fmac_f32_dpp v104, v136, v144 row_shr:2 row_mask:0xf bank_mask:0xf
	v_mov_b32_e32 v136, 0
	v_fmac_f32_dpp v104, v112, v148 row_shl:15 row_mask:0xf bank_mask:0xf
	v_fmac_f32_dpp v105, v137, v145 row_shr:2 row_mask:0xf bank_mask:0xf
	v_fmac_f32_dpp v104, v112, v144 row_shl:14 row_mask:0xf bank_mask:0xf
	v_mov_b32_e32 v137, 0
	v_fmac_f32_dpp v105, v113, v149 row_shl:15 row_mask:0xf bank_mask:0xf
	v_fmac_f32_dpp v130, v110, v146 row_shr:1 row_mask:0xf bank_mask:0xf
	v_fmac_f32_dpp v105, v113, v145 row_shl:14 row_mask:0xf bank_mask:0xf
	v_fmac_f32_dpp v130, v110, v142 row_shr:2 row_mask:0xf bank_mask:0xf
	v_fmac_f32_dpp v131, v111, v147 row_shr:1 row_mask:0xf bank_mask:0xf
	v_fmac_f32_dpp v130, v150, v146 row_shl:15 row_mask:0xf bank_mask:0xf
	v_fmac_f32_dpp v131, v111, v143 row_shr:2 row_mask:0xf bank_mask:0xf
	v_fmac_f32_dpp v130, v150, v142 row_shl:14 row_mask:0xf bank_mask:0xf
	v_fmac_f32_dpp v131, v151, v147 row_shl:15 row_mask:0xf bank_mask:0xf
	v_fmac_f32_dpp v132, v112, v148 row_shr:1 row_mask:0xf bank_mask:0xf
	v_fmac_f32_dpp v131, v151, v143 row_shl:14 row_mask:0xf bank_mask:0xf
	v_fmac_f32_dpp v132, v112, v144 row_shr:2 row_mask:0xf bank_mask:0xf
	v_fmac_f32_dpp v133, v113, v149 row_shr:1 row_mask:0xf bank_mask:0xf
	v_fmac_f32_dpp v132, v152, v148 row_shl:15 row_mask:0xf bank_mask:0xf
	v_fmac_f32_dpp v133, v113, v145 row_shr:2 row_mask:0xf bank_mask:0xf
	v_fmac_f32_dpp v132, v152, v144 row_shl:14 row_mask:0xf bank_mask:0xf
	v_fmac_f32_dpp v133, v153, v149 row_shl:15 row_mask:0xf bank_mask:0xf
	s_nop 0
	v_fmac_f32_dpp v133, v153, v145 row_shl:14 row_mask:0xf bank_mask:0xf
	ds_read_b128 v[122:125], v223
	ds_read_b128 v[126:129], v223 offset:1024
	ds_read_b128 v[142:145], v223 offset:2048
	ds_read_b128 v[110:113], v223 offset:3072
	s_and_saveexec_b64 s[48:49], s[0:1]
	v_add_u32_e32 v1, 0, v216
	v_add_u32_e32 v1, 0x20000, v1
	ds_read_b128 v[134:137], v1
	s_or_b64 exec, exec, s[48:49]
	v_mov_b32_e32 v159, v158
	v_mov_b32_e32 v161, v160
	v_pk_fma_f32 v[148:149], v[94:95], v[158:159], v[118:119] op_sel_hi:[1,0,1]
	v_pk_fma_f32 v[94:95], v[92:93], v[162:163], v[120:121] op_sel_hi:[1,0,1]
	v_pk_fma_f32 v[92:93], v[86:87], v[160:161], v[118:119] op_sel_hi:[1,0,1]
	s_waitcnt lgkmcnt(0)
	v_pk_fma_f32 v[86:87], v[114:115], v[142:143], v[110:111]
	s_nop 4
	v_fmac_f32_dpp v86, v114, v126 row_shr:1 row_mask:0xf bank_mask:0xf
	v_mov_b32_e32 v163, v162
	v_fmac_f32_dpp v86, v114, v122 row_shr:2 row_mask:0xf bank_mask:0xf
	v_fmac_f32_dpp v87, v115, v127 row_shr:1 row_mask:0xf bank_mask:0xf
	v_fmac_f32_dpp v86, v92, v126 row_shl:15 row_mask:0xf bank_mask:0xf
	v_pk_fma_f32 v[146:147], v[96:97], v[158:159], v[120:121] op_sel_hi:[1,0,1]
	v_fmac_f32_dpp v86, v92, v122 row_shl:14 row_mask:0xf bank_mask:0xf
	v_pk_fma_f32 v[96:97], v[90:91], v[162:163], v[118:119] op_sel_hi:[1,0,1]
	v_fmac_f32_dpp v87, v115, v123 row_shr:2 row_mask:0xf bank_mask:0xf
	v_pk_fma_f32 v[90:91], v[88:89], v[160:161], v[120:121] op_sel_hi:[1,0,1]
	v_fmac_f32_dpp v87, v93, v127 row_shl:15 row_mask:0xf bank_mask:0xf
	v_pk_fma_f32 v[88:89], v[116:117], v[144:145], v[112:113]
	v_fmac_f32_dpp v87, v93, v123 row_shl:14 row_mask:0xf bank_mask:0xf
	v_fmac_f32_dpp v88, v116, v128 row_shr:1 row_mask:0xf bank_mask:0xf
	v_fmac_f32_dpp v89, v117, v129 row_shr:1 row_mask:0xf bank_mask:0xf
	v_fmac_f32_dpp v88, v116, v124 row_shr:2 row_mask:0xf bank_mask:0xf
	v_fmac_f32_dpp v89, v117, v125 row_shr:2 row_mask:0xf bank_mask:0xf
	v_fmac_f32_dpp v88, v90, v128 row_shl:15 row_mask:0xf bank_mask:0xf
	v_fmac_f32_dpp v89, v91, v129 row_shl:15 row_mask:0xf bank_mask:0xf
	v_fmac_f32_dpp v88, v90, v124 row_shl:14 row_mask:0xf bank_mask:0xf
	v_fmac_f32_dpp v89, v91, v125 row_shl:14 row_mask:0xf bank_mask:0xf
	v_pk_mul_f32 v[244:245], v[88:89], s[100:101]
	v_exp_f32_e32 v244, v244
	v_exp_f32_e32 v245, v245
	v_pk_mul_f32 v[88:89], v[140:141], v[88:89]
	v_pk_add_f32 v[244:245], v[244:245], s[98:99]
	v_rcp_f32_e32 v116, v244
	v_rcp_f32_e32 v117, v245
	v_pk_mul_f32 v[244:245], v[86:87], s[100:101]
	v_exp_f32_e32 v244, v244
	v_exp_f32_e32 v245, v245
	v_pk_mul_f32 v[86:87], v[138:139], v[86:87]
	v_pk_add_f32 v[244:245], v[244:245], s[98:99]
	v_rcp_f32_e32 v114, v244
	v_rcp_f32_e32 v115, v245
	v_pk_mul_f32 v[88:89], v[88:89], v[116:117]
	v_pk_mul_f32 v[86:87], v[86:87], v[114:115]
	v_pk_fma_f32 v[114:115], v[92:93], v[142:143], v[110:111]
	s_nop 0
	v_fmac_f32_dpp v114, v92, v126 row_shr:1 row_mask:0xf bank_mask:0xf
	v_fmac_f32_dpp v115, v93, v127 row_shr:1 row_mask:0xf bank_mask:0xf
	v_fmac_f32_dpp v114, v92, v122 row_shr:2 row_mask:0xf bank_mask:0xf
	v_fma_f32 v92, v90, v144, v112
	v_fmac_f32_dpp v114, v96, v126 row_shl:15 row_mask:0xf bank_mask:0xf
	v_fmac_f32_dpp v115, v93, v123 row_shr:2 row_mask:0xf bank_mask:0xf
	v_fmac_f32_dpp v114, v96, v122 row_shl:14 row_mask:0xf bank_mask:0xf
	v_fmac_f32_dpp v115, v97, v127 row_shl:15 row_mask:0xf bank_mask:0xf
	v_fmac_f32_dpp v92, v90, v128 row_shr:1 row_mask:0xf bank_mask:0xf
	v_fmac_f32_dpp v115, v97, v123 row_shl:14 row_mask:0xf bank_mask:0xf
	v_fma_f32 v93, v91, v145, v113
	v_fmac_f32_dpp v92, v90, v124 row_shr:2 row_mask:0xf bank_mask:0xf
	v_fmac_f32_dpp v93, v91, v129 row_shr:1 row_mask:0xf bank_mask:0xf
	v_fmac_f32_dpp v92, v94, v128 row_shl:15 row_mask:0xf bank_mask:0xf
	v_fmac_f32_dpp v93, v91, v125 row_shr:2 row_mask:0xf bank_mask:0xf
	v_fmac_f32_dpp v92, v94, v124 row_shl:14 row_mask:0xf bank_mask:0xf
	v_fmac_f32_dpp v93, v95, v129 row_shl:15 row_mask:0xf bank_mask:0xf
	v_pk_mul_f32 v[106:107], v[106:107], v[114:115]
	v_fmac_f32_dpp v93, v95, v125 row_shl:14 row_mask:0xf bank_mask:0xf
	v_pk_mul_f32 v[244:245], v[92:93], s[100:101]
	v_exp_f32_e32 v244, v244
	v_exp_f32_e32 v245, v245
	v_pk_mul_f32 v[92:93], v[108:109], v[92:93]
	v_pk_add_f32 v[244:245], v[244:245], s[98:99]
	v_rcp_f32_e32 v116, v244
	v_rcp_f32_e32 v117, v245
	v_pk_mul_f32 v[244:245], v[114:115], s[100:101]
	v_exp_f32_e32 v244, v244
	v_exp_f32_e32 v245, v245
	v_pk_mul_f32 v[92:93], v[92:93], v[116:117]
	v_pk_add_f32 v[244:245], v[244:245], s[98:99]
	v_rcp_f32_e32 v90, v244
	v_rcp_f32_e32 v91, v245
	s_nop 0
	v_pk_mul_f32 v[90:91], v[106:107], v[90:91]
	v_pk_fma_f32 v[106:107], v[96:97], v[142:143], v[110:111]
	s_nop 0
	v_fmac_f32_dpp v106, v96, v126 row_shr:1 row_mask:0xf bank_mask:0xf
	v_fmac_f32_dpp v107, v97, v127 row_shr:1 row_mask:0xf bank_mask:0xf
	v_fmac_f32_dpp v106, v96, v122 row_shr:2 row_mask:0xf bank_mask:0xf
	v_fma_f32 v96, v94, v144, v112
	v_fmac_f32_dpp v106, v148, v126 row_shl:15 row_mask:0xf bank_mask:0xf
	v_fmac_f32_dpp v107, v97, v123 row_shr:2 row_mask:0xf bank_mask:0xf
	v_fmac_f32_dpp v106, v148, v122 row_shl:14 row_mask:0xf bank_mask:0xf
	v_fmac_f32_dpp v107, v149, v127 row_shl:15 row_mask:0xf bank_mask:0xf
	v_fmac_f32_dpp v96, v94, v128 row_shr:1 row_mask:0xf bank_mask:0xf
	v_fmac_f32_dpp v107, v149, v123 row_shl:14 row_mask:0xf bank_mask:0xf
	v_fma_f32 v97, v95, v145, v113
	v_fmac_f32_dpp v96, v94, v124 row_shr:2 row_mask:0xf bank_mask:0xf
	v_fmac_f32_dpp v97, v95, v129 row_shr:1 row_mask:0xf bank_mask:0xf
	v_fmac_f32_dpp v96, v146, v128 row_shl:15 row_mask:0xf bank_mask:0xf
	v_fmac_f32_dpp v97, v95, v125 row_shr:2 row_mask:0xf bank_mask:0xf
	v_fmac_f32_dpp v96, v146, v124 row_shl:14 row_mask:0xf bank_mask:0xf
	v_fmac_f32_dpp v97, v147, v129 row_shl:15 row_mask:0xf bank_mask:0xf
	v_pk_mul_f32 v[102:103], v[102:103], v[106:107]
	v_fmac_f32_dpp v97, v147, v125 row_shl:14 row_mask:0xf bank_mask:0xf
	v_pk_mul_f32 v[244:245], v[96:97], s[100:101]
	v_exp_f32_e32 v244, v244
	v_exp_f32_e32 v245, v245
	v_pk_mul_f32 v[96:97], v[104:105], v[96:97]
	v_pk_add_f32 v[244:245], v[244:245], s[98:99]
	v_rcp_f32_e32 v108, v244
	v_rcp_f32_e32 v109, v245
	v_pk_mul_f32 v[244:245], v[106:107], s[100:101]
	v_exp_f32_e32 v244, v244
	v_exp_f32_e32 v245, v245
	v_pk_mul_f32 v[96:97], v[96:97], v[108:109]
	v_pk_add_f32 v[244:245], v[244:245], s[98:99]
	v_rcp_f32_e32 v94, v244
	v_rcp_f32_e32 v95, v245
	v_pk_fma_f32 v[112:113], v[146:147], v[144:145], v[112:113]
	v_pk_mul_f32 v[94:95], v[102:103], v[94:95]
	v_pk_fma_f32 v[102:103], v[148:149], v[142:143], v[110:111]
	v_fmac_f32_dpp v112, v146, v128 row_shr:1 row_mask:0xf bank_mask:0xf
	v_fmac_f32_dpp v102, v148, v126 row_shr:1 row_mask:0xf bank_mask:0xf
	v_fmac_f32_dpp v103, v149, v127 row_shr:1 row_mask:0xf bank_mask:0xf
	v_fmac_f32_dpp v102, v148, v122 row_shr:2 row_mask:0xf bank_mask:0xf
	v_fmac_f32_dpp v103, v149, v123 row_shr:2 row_mask:0xf bank_mask:0xf
	v_fmac_f32_dpp v102, v134, v126 row_shl:15 row_mask:0xf bank_mask:0xf
	v_fmac_f32_dpp v103, v135, v127 row_shl:15 row_mask:0xf bank_mask:0xf
	v_fmac_f32_dpp v102, v134, v122 row_shl:14 row_mask:0xf bank_mask:0xf
	v_mov_b32_e32 v122, 0
	v_mul_f32_e32 v1, 0xbfb8aa3b, v102
	v_exp_f32_e32 v1, v1
	v_fmac_f32_dpp v103, v135, v123 row_shl:14 row_mask:0xf bank_mask:0xf
	v_mov_b32_e32 v123, 0
	v_fmac_f32_dpp v112, v146, v124 row_shr:2 row_mask:0xf bank_mask:0xf
	v_add_f32_e32 v1, 1.0, v1
	v_fmac_f32_dpp v112, v136, v128 row_shl:15 row_mask:0xf bank_mask:0xf
	v_rcp_f32_e32 v106, v1
	v_fmac_f32_dpp v112, v136, v124 row_shl:14 row_mask:0xf bank_mask:0xf
	v_fmac_f32_dpp v113, v147, v129 row_shr:1 row_mask:0xf bank_mask:0xf
	v_mul_f32_e32 v1, 0xbfb8aa3b, v103
	v_fmac_f32_dpp v113, v147, v125 row_shr:2 row_mask:0xf bank_mask:0xf
	v_exp_f32_e32 v1, v1
	v_fmac_f32_dpp v113, v137, v129 row_shl:15 row_mask:0xf bank_mask:0xf
	v_add_f32_e32 v1, 1.0, v1
	v_fmac_f32_dpp v113, v137, v125 row_shl:14 row_mask:0xf bank_mask:0xf
	v_pk_mul_f32 v[244:245], v[112:113], s[100:101]
	v_exp_f32_e32 v244, v244
	v_exp_f32_e32 v245, v245
	v_rcp_f32_e32 v107, v1
	v_pk_add_f32 v[244:245], v[244:245], s[98:99]
	v_rcp_f32_e32 v104, v244
	v_rcp_f32_e32 v105, v245
	v_pk_mul_f32 v[108:109], v[132:133], v[112:113]
	v_pk_mul_f32 v[102:103], v[130:131], v[102:103]
	v_pk_mul_f32 v[104:105], v[108:109], v[104:105]
	v_pk_mul_f32 v[102:103], v[102:103], v[106:107]
	v_mov_b32_e32 v124, 0
	ds_read_b128 v[114:117], v223 offset:528
	ds_read_b128 v[118:121], v223 offset:1552
	ds_read_b128 v[126:129], v223 offset:2576
	ds_read_b128 v[106:109], v223 offset:3600
	v_mov_b32_e32 v125, 0
	s_and_saveexec_b64 s[48:49], s[30:31]
	v_add_u32_e32 v1, s91, v217
	ds_read_b128 v[122:125], v1 offset:512
	s_or_b64 exec, exec, s[48:49]
	v_pk_fma_f32 v[76:77], v[76:77], v[194:195], v[56:57] op_sel_hi:[1,0,1]
	v_pk_fma_f32 v[130:131], v[72:73], v[196:197], v[56:57] op_sel_hi:[1,0,1]
	s_waitcnt lgkmcnt(0)
	v_pk_fma_f32 v[110:111], v[98:99], v[126:127], v[106:107]
	s_nop 4
	v_fmac_f32_dpp v110, v98, v118 row_shr:1 row_mask:0xf bank_mask:0xf
	v_pk_fma_f32 v[66:67], v[66:67], v[198:199], v[54:55]
	v_fmac_f32_dpp v110, v98, v114 row_shr:2 row_mask:0xf bank_mask:0xf
	v_pk_fma_f32 v[112:113], v[100:101], v[128:129], v[108:109]
	v_fmac_f32_dpp v110, v66, v118 row_shl:15 row_mask:0xf bank_mask:0xf
	v_fmac_f32_dpp v111, v99, v119 row_shr:1 row_mask:0xf bank_mask:0xf
	v_fmac_f32_dpp v110, v66, v114 row_shl:14 row_mask:0xf bank_mask:0xf
	v_pk_fma_f32 v[132:133], v[70:71], v[196:197], v[54:55]
	v_fmac_f32_dpp v111, v99, v115 row_shr:2 row_mask:0xf bank_mask:0xf
	v_fmac_f32_dpp v112, v100, v120 row_shr:1 row_mask:0xf bank_mask:0xf
	v_fmac_f32_dpp v111, v67, v119 row_shl:15 row_mask:0xf bank_mask:0xf
	v_pk_fma_f32 v[68:69], v[68:69], v[198:199], v[56:57] op_sel_hi:[1,0,1]
	v_fmac_f32_dpp v111, v67, v115 row_shl:14 row_mask:0xf bank_mask:0xf
	v_fmac_f32_dpp v112, v100, v116 row_shr:2 row_mask:0xf bank_mask:0xf
	v_pk_fma_f32 v[70:71], v[66:67], v[126:127], v[106:107]
	v_fmac_f32_dpp v112, v68, v120 row_shl:15 row_mask:0xf bank_mask:0xf
	v_fmac_f32_dpp v113, v101, v121 row_shr:1 row_mask:0xf bank_mask:0xf
	v_fmac_f32_dpp v112, v68, v116 row_shl:14 row_mask:0xf bank_mask:0xf
	v_fmac_f32_dpp v113, v101, v117 row_shr:2 row_mask:0xf bank_mask:0xf
	v_pk_fma_f32 v[72:73], v[68:69], v[128:129], v[108:109]
	v_fmac_f32_dpp v113, v69, v121 row_shl:15 row_mask:0xf bank_mask:0xf
	v_pk_fma_f32 v[74:75], v[74:75], v[194:195], v[54:55]
	v_fmac_f32_dpp v113, v69, v117 row_shl:14 row_mask:0xf bank_mask:0xf
	v_fmac_f32_dpp v70, v66, v118 row_shr:1 row_mask:0xf bank_mask:0xf
	v_fmac_f32_dpp v71, v67, v119 row_shr:1 row_mask:0xf bank_mask:0xf
	v_fmac_f32_dpp v70, v66, v114 row_shr:2 row_mask:0xf bank_mask:0xf
	v_fma_f32 v66, v132, v126, v106
	v_fmac_f32_dpp v70, v132, v118 row_shl:15 row_mask:0xf bank_mask:0xf
	v_fmac_f32_dpp v71, v67, v115 row_shr:2 row_mask:0xf bank_mask:0xf
	v_fmac_f32_dpp v70, v132, v114 row_shl:14 row_mask:0xf bank_mask:0xf
	v_fma_f32 v67, v133, v127, v107
	v_fmac_f32_dpp v71, v133, v119 row_shl:15 row_mask:0xf bank_mask:0xf
	v_pk_fma_f32 v[106:107], v[74:75], v[126:127], v[106:107]
	v_fmac_f32_dpp v71, v133, v115 row_shl:14 row_mask:0xf bank_mask:0xf
	v_fmac_f32_dpp v72, v68, v120 row_shr:1 row_mask:0xf bank_mask:0xf
	v_fmac_f32_dpp v73, v69, v121 row_shr:1 row_mask:0xf bank_mask:0xf
	v_fmac_f32_dpp v72, v68, v116 row_shr:2 row_mask:0xf bank_mask:0xf
	v_fma_f32 v68, v130, v128, v108
	v_fmac_f32_dpp v72, v130, v120 row_shl:15 row_mask:0xf bank_mask:0xf
	v_fmac_f32_dpp v73, v69, v117 row_shr:2 row_mask:0xf bank_mask:0xf
	v_fmac_f32_dpp v72, v130, v116 row_shl:14 row_mask:0xf bank_mask:0xf
	v_fma_f32 v69, v131, v129, v109
	v_fmac_f32_dpp v73, v131, v121 row_shl:15 row_mask:0xf bank_mask:0xf
	v_pk_fma_f32 v[108:109], v[76:77], v[128:129], v[108:109]
	v_fmac_f32_dpp v73, v131, v117 row_shl:14 row_mask:0xf bank_mask:0xf
	v_fmac_f32_dpp v66, v132, v118 row_shr:1 row_mask:0xf bank_mask:0xf
	v_fmac_f32_dpp v67, v133, v119 row_shr:1 row_mask:0xf bank_mask:0xf
	v_fmac_f32_dpp v66, v132, v114 row_shr:2 row_mask:0xf bank_mask:0xf
	v_fmac_f32_dpp v67, v133, v115 row_shr:2 row_mask:0xf bank_mask:0xf
	v_fmac_f32_dpp v66, v74, v118 row_shl:15 row_mask:0xf bank_mask:0xf
	v_fmac_f32_dpp v67, v75, v119 row_shl:15 row_mask:0xf bank_mask:0xf
	v_fmac_f32_dpp v66, v74, v114 row_shl:14 row_mask:0xf bank_mask:0xf
	v_fmac_f32_dpp v67, v75, v115 row_shl:14 row_mask:0xf bank_mask:0xf
	v_fmac_f32_dpp v68, v130, v120 row_shr:1 row_mask:0xf bank_mask:0xf
	v_fmac_f32_dpp v69, v131, v121 row_shr:1 row_mask:0xf bank_mask:0xf
	v_fmac_f32_dpp v68, v130, v116 row_shr:2 row_mask:0xf bank_mask:0xf
	v_fmac_f32_dpp v69, v131, v117 row_shr:2 row_mask:0xf bank_mask:0xf
	v_fmac_f32_dpp v68, v76, v120 row_shl:15 row_mask:0xf bank_mask:0xf
	v_fmac_f32_dpp v69, v77, v121 row_shl:15 row_mask:0xf bank_mask:0xf
	v_fmac_f32_dpp v68, v76, v116 row_shl:14 row_mask:0xf bank_mask:0xf
	v_fmac_f32_dpp v69, v77, v117 row_shl:14 row_mask:0xf bank_mask:0xf
	v_fmac_f32_dpp v106, v74, v118 row_shr:1 row_mask:0xf bank_mask:0xf
	v_fmac_f32_dpp v107, v75, v119 row_shr:1 row_mask:0xf bank_mask:0xf
	v_fmac_f32_dpp v106, v74, v114 row_shr:2 row_mask:0xf bank_mask:0xf
	v_fmac_f32_dpp v107, v75, v115 row_shr:2 row_mask:0xf bank_mask:0xf
	v_fmac_f32_dpp v106, v122, v118 row_shl:15 row_mask:0xf bank_mask:0xf
	v_fmac_f32_dpp v107, v123, v119 row_shl:15 row_mask:0xf bank_mask:0xf
	v_fmac_f32_dpp v106, v122, v114 row_shl:14 row_mask:0xf bank_mask:0xf
	v_fmac_f32_dpp v107, v123, v115 row_shl:14 row_mask:0xf bank_mask:0xf
	v_fmac_f32_dpp v108, v76, v120 row_shr:1 row_mask:0xf bank_mask:0xf
	v_fmac_f32_dpp v109, v77, v121 row_shr:1 row_mask:0xf bank_mask:0xf
	v_fmac_f32_dpp v108, v76, v116 row_shr:2 row_mask:0xf bank_mask:0xf
	v_fmac_f32_dpp v109, v77, v117 row_shr:2 row_mask:0xf bank_mask:0xf
	v_fmac_f32_dpp v108, v124, v120 row_shl:15 row_mask:0xf bank_mask:0xf
	v_fmac_f32_dpp v109, v125, v121 row_shl:15 row_mask:0xf bank_mask:0xf
	v_fmac_f32_dpp v108, v124, v116 row_shl:14 row_mask:0xf bank_mask:0xf
	v_fmac_f32_dpp v109, v125, v117 row_shl:14 row_mask:0xf bank_mask:0xf
	s_and_saveexec_b64 s[48:49], s[34:35]
	s_cbranch_execz .LBB0_579
	v_or_b32_e32 v74, 4, v200
	v_ashrrev_i32_e32 v75, 31, v74
	v_lshl_add_u64 v[74:75], v[74:75], 2, v[168:169]
	v_add_co_u32_e32 v74, vcc, 0x2000, v74
	s_nop 1
	v_addc_co_u32_e32 v75, vcc, 0, v75, vcc
	global_store_dwordx4 v[74:75], v[106:109], off offset:3072
.LBB0_579:
	s_or_b64 exec, exec, s[48:49]
	ds_read_b128 v[98:101], v223 offset:16
	ds_read_b128 v[114:117], v223 offset:1040
	ds_read_b128 v[122:125], v223 offset:2064
	ds_read_b128 v[74:77], v223 offset:3088
	v_mov_b32_e32 v118, 0
	v_mov_b32_e32 v119, 0
	v_mov_b32_e32 v120, 0
	v_mov_b32_e32 v121, 0
	s_and_saveexec_b64 s[48:49], s[30:31]
	v_add_u32_e32 v1, 0, v217
	v_add_u32_e32 v1, 0x20000, v1
	ds_read_b128 v[118:121], v1
	s_or_b64 exec, exec, s[48:49]
	v_pk_fma_f32 v[128:129], v[42:43], v[194:195], v[30:31]
	v_pk_fma_f32 v[42:43], v[40:41], v[196:197], v[32:33] op_sel_hi:[1,0,1]
	v_pk_fma_f32 v[40:41], v[34:35], v[198:199], v[30:31]
	s_waitcnt lgkmcnt(0)
	v_pk_fma_f32 v[34:35], v[82:83], v[122:123], v[74:75]
	s_nop 4
	v_fmac_f32_dpp v34, v82, v114 row_shr:1 row_mask:0xf bank_mask:0xf
	v_fmac_f32_dpp v35, v83, v115 row_shr:1 row_mask:0xf bank_mask:0xf
	v_fmac_f32_dpp v34, v82, v98 row_shr:2 row_mask:0xf bank_mask:0xf
	v_pk_fma_f32 v[126:127], v[44:45], v[194:195], v[32:33] op_sel_hi:[1,0,1]
	v_fmac_f32_dpp v34, v40, v114 row_shl:15 row_mask:0xf bank_mask:0xf
	v_pk_fma_f32 v[44:45], v[38:39], v[196:197], v[30:31]
	v_fmac_f32_dpp v34, v40, v98 row_shl:14 row_mask:0xf bank_mask:0xf
	v_fmac_f32_dpp v35, v83, v99 row_shr:2 row_mask:0xf bank_mask:0xf
	v_pk_fma_f32 v[38:39], v[36:37], v[198:199], v[32:33] op_sel_hi:[1,0,1]
	v_fmac_f32_dpp v35, v41, v115 row_shl:15 row_mask:0xf bank_mask:0xf
	v_pk_fma_f32 v[36:37], v[84:85], v[124:125], v[76:77]
	v_fmac_f32_dpp v35, v41, v99 row_shl:14 row_mask:0xf bank_mask:0xf
	v_fmac_f32_dpp v36, v84, v116 row_shr:1 row_mask:0xf bank_mask:0xf
	v_fmac_f32_dpp v37, v85, v117 row_shr:1 row_mask:0xf bank_mask:0xf
	v_fmac_f32_dpp v36, v84, v100 row_shr:2 row_mask:0xf bank_mask:0xf
	v_fmac_f32_dpp v37, v85, v101 row_shr:2 row_mask:0xf bank_mask:0xf
	v_fmac_f32_dpp v36, v38, v116 row_shl:15 row_mask:0xf bank_mask:0xf
	v_fmac_f32_dpp v37, v39, v117 row_shl:15 row_mask:0xf bank_mask:0xf
	v_fmac_f32_dpp v36, v38, v100 row_shl:14 row_mask:0xf bank_mask:0xf
	v_fmac_f32_dpp v37, v39, v101 row_shl:14 row_mask:0xf bank_mask:0xf
	v_pk_mul_f32 v[244:245], v[36:37], s[100:101]
	v_exp_f32_e32 v244, v244
	v_exp_f32_e32 v245, v245
	v_pk_mul_f32 v[36:37], v[112:113], v[36:37]
	v_pk_add_f32 v[244:245], v[244:245], s[98:99]
	v_rcp_f32_e32 v84, v244
	v_rcp_f32_e32 v85, v245
	v_pk_mul_f32 v[244:245], v[34:35], s[100:101]
	v_exp_f32_e32 v244, v244
	v_exp_f32_e32 v245, v245
	v_pk_mul_f32 v[34:35], v[110:111], v[34:35]
	v_pk_add_f32 v[244:245], v[244:245], s[98:99]
	v_rcp_f32_e32 v82, v244
	v_rcp_f32_e32 v83, v245
	v_pk_mul_f32 v[36:37], v[36:37], v[84:85]
	v_pk_mul_f32 v[34:35], v[34:35], v[82:83]
	v_pk_fma_f32 v[82:83], v[40:41], v[122:123], v[74:75]
	s_nop 0
	v_fmac_f32_dpp v82, v40, v114 row_shr:1 row_mask:0xf bank_mask:0xf
	v_fmac_f32_dpp v83, v41, v115 row_shr:1 row_mask:0xf bank_mask:0xf
	v_fmac_f32_dpp v82, v40, v98 row_shr:2 row_mask:0xf bank_mask:0xf
	v_fma_f32 v40, v38, v124, v76
	v_fmac_f32_dpp v82, v44, v114 row_shl:15 row_mask:0xf bank_mask:0xf
	v_fmac_f32_dpp v83, v41, v99 row_shr:2 row_mask:0xf bank_mask:0xf
	v_fmac_f32_dpp v82, v44, v98 row_shl:14 row_mask:0xf bank_mask:0xf
	v_fmac_f32_dpp v83, v45, v115 row_shl:15 row_mask:0xf bank_mask:0xf
	v_fmac_f32_dpp v40, v38, v116 row_shr:1 row_mask:0xf bank_mask:0xf
	v_fmac_f32_dpp v83, v45, v99 row_shl:14 row_mask:0xf bank_mask:0xf
	v_fma_f32 v41, v39, v125, v77
	v_fmac_f32_dpp v40, v38, v100 row_shr:2 row_mask:0xf bank_mask:0xf
	v_fmac_f32_dpp v41, v39, v117 row_shr:1 row_mask:0xf bank_mask:0xf
	v_fmac_f32_dpp v40, v42, v116 row_shl:15 row_mask:0xf bank_mask:0xf
	v_fmac_f32_dpp v41, v39, v101 row_shr:2 row_mask:0xf bank_mask:0xf
	v_fmac_f32_dpp v40, v42, v100 row_shl:14 row_mask:0xf bank_mask:0xf
	v_fmac_f32_dpp v41, v43, v117 row_shl:15 row_mask:0xf bank_mask:0xf
	v_pk_mul_f32 v[70:71], v[70:71], v[82:83]
	v_fmac_f32_dpp v41, v43, v101 row_shl:14 row_mask:0xf bank_mask:0xf
	v_pk_mul_f32 v[244:245], v[40:41], s[100:101]
	v_exp_f32_e32 v244, v244
	v_exp_f32_e32 v245, v245
	v_pk_mul_f32 v[40:41], v[72:73], v[40:41]
	v_pk_add_f32 v[244:245], v[244:245], s[98:99]
	v_rcp_f32_e32 v84, v244
	v_rcp_f32_e32 v85, v245
	v_pk_mul_f32 v[244:245], v[82:83], s[100:101]
	v_exp_f32_e32 v244, v244
	v_exp_f32_e32 v245, v245
	v_pk_mul_f32 v[40:41], v[40:41], v[84:85]
	v_pk_add_f32 v[244:245], v[244:245], s[98:99]
	v_rcp_f32_e32 v38, v244
	v_rcp_f32_e32 v39, v245
	s_nop 0
	v_pk_mul_f32 v[38:39], v[70:71], v[38:39]
	v_pk_fma_f32 v[70:71], v[44:45], v[122:123], v[74:75]
	v_pk_fma_f32 v[74:75], v[128:129], v[122:123], v[74:75]
	v_fmac_f32_dpp v70, v44, v114 row_shr:1 row_mask:0xf bank_mask:0xf
	v_fmac_f32_dpp v71, v45, v115 row_shr:1 row_mask:0xf bank_mask:0xf
	v_fmac_f32_dpp v70, v44, v98 row_shr:2 row_mask:0xf bank_mask:0xf
	v_fma_f32 v44, v42, v124, v76
	v_fmac_f32_dpp v70, v128, v114 row_shl:15 row_mask:0xf bank_mask:0xf
	v_fmac_f32_dpp v71, v45, v99 row_shr:2 row_mask:0xf bank_mask:0xf
	v_fmac_f32_dpp v70, v128, v98 row_shl:14 row_mask:0xf bank_mask:0xf
	v_mul_f32_e32 v1, 0xbfb8aa3b, v70
	v_fmac_f32_dpp v71, v129, v115 row_shl:15 row_mask:0xf bank_mask:0xf
	v_exp_f32_e32 v1, v1
	v_fmac_f32_dpp v71, v129, v99 row_shl:14 row_mask:0xf bank_mask:0xf
	v_fmac_f32_dpp v44, v42, v116 row_shr:1 row_mask:0xf bank_mask:0xf
	v_fma_f32 v45, v43, v125, v77
	v_fmac_f32_dpp v44, v42, v100 row_shr:2 row_mask:0xf bank_mask:0xf
	v_add_f32_e32 v1, 1.0, v1
	v_fmac_f32_dpp v44, v126, v116 row_shl:15 row_mask:0xf bank_mask:0xf
	v_rcp_f32_e32 v42, v1
	v_fmac_f32_dpp v44, v126, v100 row_shl:14 row_mask:0xf bank_mask:0xf
	v_fmac_f32_dpp v45, v43, v117 row_shr:1 row_mask:0xf bank_mask:0xf
	v_mul_f32_e32 v1, 0xbfb8aa3b, v71
	v_fmac_f32_dpp v45, v43, v101 row_shr:2 row_mask:0xf bank_mask:0xf
	v_exp_f32_e32 v1, v1
	v_fmac_f32_dpp v45, v127, v117 row_shl:15 row_mask:0xf bank_mask:0xf
	v_add_f32_e32 v1, 1.0, v1
	v_fmac_f32_dpp v45, v127, v101 row_shl:14 row_mask:0xf bank_mask:0xf
	v_pk_mul_f32 v[244:245], v[44:45], s[100:101]
	v_exp_f32_e32 v244, v244
	v_exp_f32_e32 v245, v245
	v_rcp_f32_e32 v43, v1
	v_pk_add_f32 v[244:245], v[244:245], s[98:99]
	v_rcp_f32_e32 v72, v244
	v_rcp_f32_e32 v73, v245
	v_pk_mul_f32 v[44:45], v[68:69], v[44:45]
	v_pk_mul_f32 v[66:67], v[66:67], v[70:71]
	v_pk_mul_f32 v[44:45], v[44:45], v[72:73]
	v_pk_mul_f32 v[42:43], v[66:67], v[42:43]
	v_pk_fma_f32 v[76:77], v[126:127], v[124:125], v[76:77]
	v_fmac_f32_dpp v74, v128, v114 row_shr:1 row_mask:0xf bank_mask:0xf
	v_fmac_f32_dpp v75, v129, v115 row_shr:1 row_mask:0xf bank_mask:0xf
	v_fmac_f32_dpp v74, v128, v98 row_shr:2 row_mask:0xf bank_mask:0xf
	v_fmac_f32_dpp v75, v129, v99 row_shr:2 row_mask:0xf bank_mask:0xf
	v_fmac_f32_dpp v74, v118, v114 row_shl:15 row_mask:0xf bank_mask:0xf
	v_fmac_f32_dpp v75, v119, v115 row_shl:15 row_mask:0xf bank_mask:0xf
	v_fmac_f32_dpp v74, v118, v98 row_shl:14 row_mask:0xf bank_mask:0xf
	v_fmac_f32_dpp v75, v119, v99 row_shl:14 row_mask:0xf bank_mask:0xf
	v_fmac_f32_dpp v76, v126, v116 row_shr:1 row_mask:0xf bank_mask:0xf
	v_fmac_f32_dpp v77, v127, v117 row_shr:1 row_mask:0xf bank_mask:0xf
	v_fmac_f32_dpp v76, v126, v100 row_shr:2 row_mask:0xf bank_mask:0xf
	v_fmac_f32_dpp v77, v127, v101 row_shr:2 row_mask:0xf bank_mask:0xf
	v_fmac_f32_dpp v76, v120, v116 row_shl:15 row_mask:0xf bank_mask:0xf
	v_fmac_f32_dpp v77, v121, v117 row_shl:15 row_mask:0xf bank_mask:0xf
	v_fmac_f32_dpp v76, v120, v100 row_shl:14 row_mask:0xf bank_mask:0xf
	v_fmac_f32_dpp v77, v121, v101 row_shl:14 row_mask:0xf bank_mask:0xf
	s_and_saveexec_b64 s[48:49], s[34:35]
	s_cbranch_execz .LBB0_583
	global_store_dwordx4 v[166:167], v[74:77], off offset:16
.LBB0_583:
	s_or_b64 exec, exec, s[48:49]
	v_mul_f32_e32 v67, 0xbfb8aa3b, v76
	v_exp_f32_e32 v1, v67
	v_mul_f32_e32 v67, 0xbfb8aa3b, v77
	v_exp_f32_e32 v67, v67
	v_add_f32_e32 v1, 1.0, v1
	v_rcp_f32_e32 v68, v1
	v_add_f32_e32 v1, 1.0, v67
	v_rcp_f32_e32 v69, v1
	v_pk_mul_f32 v[244:245], v[74:75], s[100:101]
	v_exp_f32_e32 v244, v244
	v_exp_f32_e32 v245, v245
	v_pk_mul_f32 v[70:71], v[108:109], v[76:77]
	v_pk_add_f32 v[244:245], v[244:245], s[98:99]
	v_rcp_f32_e32 v66, v244
	v_rcp_f32_e32 v67, v245
	v_pk_mul_f32 v[72:73], v[106:107], v[74:75]
	v_pk_mul_f32 v[68:69], v[70:71], v[68:69]
	v_pk_mul_f32 v[66:67], v[72:73], v[66:67]
	v_mov_b32_e32 v74, 0
	ds_read_b128 v[98:101], v223 offset:528
	ds_read_b128 v[106:109], v223 offset:1552
	ds_read_b128 v[114:117], v223 offset:2576
	ds_read_b128 v[70:73], v223 offset:3600
	v_mov_b32_e32 v110, 0
	v_mov_b32_e32 v111, 0
	v_mov_b32_e32 v112, 0
	v_mov_b32_e32 v113, 0
	s_and_saveexec_b64 s[48:49], s[0:1]
	v_add_u32_e32 v1, s91, v218
	ds_read_b128 v[110:113], v1 offset:512
	s_or_b64 exec, exec, s[48:49]
	s_waitcnt lgkmcnt(0)
	v_pk_fma_f32 v[82:83], v[58:59], v[114:115], v[70:71]
	s_nop 4
	v_fmac_f32_dpp v82, v58, v106 row_shr:1 row_mask:0xf bank_mask:0xf
	v_pk_fma_f32 v[14:15], v[14:15], v[160:161], v[54:55]
	v_fmac_f32_dpp v82, v58, v98 row_shr:2 row_mask:0xf bank_mask:0xf
	v_pk_fma_f32 v[84:85], v[60:61], v[116:117], v[72:73]
	v_fmac_f32_dpp v82, v14, v106 row_shl:15 row_mask:0xf bank_mask:0xf
	v_fmac_f32_dpp v83, v59, v107 row_shr:1 row_mask:0xf bank_mask:0xf
	v_fmac_f32_dpp v82, v14, v98 row_shl:14 row_mask:0xf bank_mask:0xf
	v_mov_b32_e32 v122, v160
	v_fmac_f32_dpp v83, v59, v99 row_shr:2 row_mask:0xf bank_mask:0xf
	v_mov_b32_e32 v123, v160
	v_fmac_f32_dpp v83, v15, v107 row_shl:15 row_mask:0xf bank_mask:0xf
	v_pk_fma_f32 v[16:17], v[16:17], v[160:161], v[56:57] op_sel_hi:[1,0,1]
	v_fmac_f32_dpp v83, v15, v99 row_shl:14 row_mask:0xf bank_mask:0xf
	v_fmac_f32_dpp v84, v60, v108 row_shr:1 row_mask:0xf bank_mask:0xf
	v_pk_fma_f32 v[124:125], v[18:19], v[162:163], v[54:55]
	v_fmac_f32_dpp v84, v60, v100 row_shr:2 row_mask:0xf bank_mask:0xf
	v_pk_fma_f32 v[18:19], v[14:15], v[114:115], v[70:71]
	v_fmac_f32_dpp v84, v16, v108 row_shl:15 row_mask:0xf bank_mask:0xf
	v_fmac_f32_dpp v85, v61, v109 row_shr:1 row_mask:0xf bank_mask:0xf
	v_fmac_f32_dpp v84, v16, v100 row_shl:14 row_mask:0xf bank_mask:0xf
	v_fmac_f32_dpp v85, v61, v101 row_shr:2 row_mask:0xf bank_mask:0xf
	v_mov_b32_e32 v120, v162
	v_fmac_f32_dpp v85, v17, v109 row_shl:15 row_mask:0xf bank_mask:0xf
	v_mov_b32_e32 v121, v162
	v_fmac_f32_dpp v85, v17, v101 row_shl:14 row_mask:0xf bank_mask:0xf
	v_pk_fma_f32 v[76:77], v[20:21], v[162:163], v[56:57] op_sel_hi:[1,0,1]
	v_fmac_f32_dpp v18, v14, v106 row_shr:1 row_mask:0xf bank_mask:0xf
	v_pk_fma_f32 v[20:21], v[16:17], v[116:117], v[72:73]
	v_fmac_f32_dpp v18, v14, v98 row_shr:2 row_mask:0xf bank_mask:0xf
	v_fmac_f32_dpp v19, v15, v107 row_shr:1 row_mask:0xf bank_mask:0xf
	v_fmac_f32_dpp v18, v124, v106 row_shl:15 row_mask:0xf bank_mask:0xf
	v_pk_fma_f32 v[22:23], v[22:23], v[158:159], v[54:55]
	v_fmac_f32_dpp v18, v124, v98 row_shl:14 row_mask:0xf bank_mask:0xf
	v_fmac_f32_dpp v19, v15, v99 row_shr:2 row_mask:0xf bank_mask:0xf
	v_pk_fma_f32 v[14:15], v[124:125], v[114:115], v[70:71]
	v_fmac_f32_dpp v19, v125, v107 row_shl:15 row_mask:0xf bank_mask:0xf
	v_mov_b32_e32 v118, v158
	v_fmac_f32_dpp v19, v125, v99 row_shl:14 row_mask:0xf bank_mask:0xf
	v_fmac_f32_dpp v20, v16, v108 row_shr:1 row_mask:0xf bank_mask:0xf
	v_mov_b32_e32 v119, v158
	v_fmac_f32_dpp v20, v16, v100 row_shr:2 row_mask:0xf bank_mask:0xf
	v_pk_fma_f32 v[24:25], v[24:25], v[158:159], v[56:57] op_sel_hi:[1,0,1]
	v_fmac_f32_dpp v20, v76, v108 row_shl:15 row_mask:0xf bank_mask:0xf
	v_fmac_f32_dpp v21, v17, v109 row_shr:1 row_mask:0xf bank_mask:0xf
	v_fmac_f32_dpp v20, v76, v100 row_shl:14 row_mask:0xf bank_mask:0xf
	v_pk_fma_f32 v[70:71], v[22:23], v[114:115], v[70:71]
	v_fmac_f32_dpp v21, v17, v101 row_shr:2 row_mask:0xf bank_mask:0xf
	v_pk_fma_f32 v[16:17], v[76:77], v[116:117], v[72:73]
	v_fmac_f32_dpp v21, v77, v109 row_shl:15 row_mask:0xf bank_mask:0xf
	v_pk_fma_f32 v[72:73], v[24:25], v[116:117], v[72:73]
	v_fmac_f32_dpp v21, v77, v101 row_shl:14 row_mask:0xf bank_mask:0xf
	v_fmac_f32_dpp v14, v124, v106 row_shr:1 row_mask:0xf bank_mask:0xf
	v_mov_b32_e32 v75, 0
	v_fmac_f32_dpp v14, v124, v98 row_shr:2 row_mask:0xf bank_mask:0xf
	v_fmac_f32_dpp v15, v125, v107 row_shr:1 row_mask:0xf bank_mask:0xf
	v_fmac_f32_dpp v14, v22, v106 row_shl:15 row_mask:0xf bank_mask:0xf
	v_fmac_f32_dpp v15, v125, v99 row_shr:2 row_mask:0xf bank_mask:0xf
	v_fmac_f32_dpp v14, v22, v98 row_shl:14 row_mask:0xf bank_mask:0xf
	v_fmac_f32_dpp v15, v23, v107 row_shl:15 row_mask:0xf bank_mask:0xf
	v_fmac_f32_dpp v16, v76, v108 row_shr:1 row_mask:0xf bank_mask:0xf
	v_fmac_f32_dpp v15, v23, v99 row_shl:14 row_mask:0xf bank_mask:0xf
	v_fmac_f32_dpp v16, v76, v100 row_shr:2 row_mask:0xf bank_mask:0xf
	v_mov_b32_e32 v76, 0
	v_fmac_f32_dpp v16, v24, v108 row_shl:15 row_mask:0xf bank_mask:0xf
	v_fmac_f32_dpp v17, v77, v109 row_shr:1 row_mask:0xf bank_mask:0xf
	v_fmac_f32_dpp v16, v24, v100 row_shl:14 row_mask:0xf bank_mask:0xf
	v_fmac_f32_dpp v17, v77, v101 row_shr:2 row_mask:0xf bank_mask:0xf
	v_mov_b32_e32 v77, 0
	v_fmac_f32_dpp v17, v25, v109 row_shl:15 row_mask:0xf bank_mask:0xf
	v_fmac_f32_dpp v70, v22, v106 row_shr:1 row_mask:0xf bank_mask:0xf
	v_fmac_f32_dpp v17, v25, v101 row_shl:14 row_mask:0xf bank_mask:0xf
	v_fmac_f32_dpp v70, v22, v98 row_shr:2 row_mask:0xf bank_mask:0xf
	v_fmac_f32_dpp v71, v23, v107 row_shr:1 row_mask:0xf bank_mask:0xf
	v_fmac_f32_dpp v70, v110, v106 row_shl:15 row_mask:0xf bank_mask:0xf
	v_fmac_f32_dpp v71, v23, v99 row_shr:2 row_mask:0xf bank_mask:0xf
	v_fmac_f32_dpp v70, v110, v98 row_shl:14 row_mask:0xf bank_mask:0xf
	v_fmac_f32_dpp v71, v111, v107 row_shl:15 row_mask:0xf bank_mask:0xf
	v_fmac_f32_dpp v72, v24, v108 row_shr:1 row_mask:0xf bank_mask:0xf
	v_fmac_f32_dpp v71, v111, v99 row_shl:14 row_mask:0xf bank_mask:0xf
	v_fmac_f32_dpp v72, v24, v100 row_shr:2 row_mask:0xf bank_mask:0xf
	v_fmac_f32_dpp v73, v25, v109 row_shr:1 row_mask:0xf bank_mask:0xf
	v_fmac_f32_dpp v72, v112, v108 row_shl:15 row_mask:0xf bank_mask:0xf
	v_fmac_f32_dpp v73, v25, v101 row_shr:2 row_mask:0xf bank_mask:0xf
	v_fmac_f32_dpp v72, v112, v100 row_shl:14 row_mask:0xf bank_mask:0xf
	v_fmac_f32_dpp v73, v113, v109 row_shl:15 row_mask:0xf bank_mask:0xf
	s_nop 0
	v_fmac_f32_dpp v73, v113, v101 row_shl:14 row_mask:0xf bank_mask:0xf
	ds_read_b128 v[54:57], v223 offset:16
	ds_read_b128 v[58:61], v223 offset:1040
	ds_read_b128 v[98:101], v223 offset:2064
	ds_read_b128 v[22:25], v223 offset:3088
	s_and_saveexec_b64 s[48:49], s[0:1]
	v_add_u32_e32 v1, 0, v218
	v_add_u32_e32 v1, 0x20000, v1
	ds_read_b128 v[74:77], v1
	s_or_b64 exec, exec, s[48:49]
	v_pk_fma_f32 v[106:107], v[8:9], v[162:163], v[32:33] op_sel_hi:[1,0,1]
	v_pk_fma_f32 v[8:9], v[2:3], v[160:161], v[30:31]
	s_waitcnt lgkmcnt(0)
	v_pk_fma_f32 v[2:3], v[26:27], v[98:99], v[22:23]
	s_nop 4
	v_fmac_f32_dpp v2, v26, v58 row_shr:1 row_mask:0xf bank_mask:0xf
	v_pk_fma_f32 v[108:109], v[6:7], v[162:163], v[30:31]
	v_fmac_f32_dpp v2, v26, v54 row_shr:2 row_mask:0xf bank_mask:0xf
	v_pk_fma_f32 v[6:7], v[4:5], v[160:161], v[32:33] op_sel_hi:[1,0,1]
	v_fmac_f32_dpp v2, v8, v58 row_shl:15 row_mask:0xf bank_mask:0xf
	v_fmac_f32_dpp v3, v27, v59 row_shr:1 row_mask:0xf bank_mask:0xf
	v_fmac_f32_dpp v2, v8, v54 row_shl:14 row_mask:0xf bank_mask:0xf
	v_pk_fma_f32 v[4:5], v[28:29], v[100:101], v[24:25]
	v_fmac_f32_dpp v3, v27, v55 row_shr:2 row_mask:0xf bank_mask:0xf
	v_fmac_f32_dpp v4, v28, v60 row_shr:1 row_mask:0xf bank_mask:0xf
	v_fmac_f32_dpp v3, v9, v59 row_shl:15 row_mask:0xf bank_mask:0xf
	v_fmac_f32_dpp v4, v28, v56 row_shr:2 row_mask:0xf bank_mask:0xf
	v_fmac_f32_dpp v3, v9, v55 row_shl:14 row_mask:0xf bank_mask:0xf
	v_fmac_f32_dpp v4, v6, v60 row_shl:15 row_mask:0xf bank_mask:0xf
	v_fmac_f32_dpp v5, v29, v61 row_shr:1 row_mask:0xf bank_mask:0xf
	v_fmac_f32_dpp v4, v6, v56 row_shl:14 row_mask:0xf bank_mask:0xf
	v_fmac_f32_dpp v5, v29, v57 row_shr:2 row_mask:0xf bank_mask:0xf
	v_pk_fma_f32 v[10:11], v[10:11], v[158:159], v[30:31]
	v_fmac_f32_dpp v5, v7, v61 row_shl:15 row_mask:0xf bank_mask:0xf
	v_pk_fma_f32 v[12:13], v[12:13], v[158:159], v[32:33] op_sel_hi:[1,0,1]
	v_fmac_f32_dpp v5, v7, v57 row_shl:14 row_mask:0xf bank_mask:0xf
	v_pk_mul_f32 v[244:245], v[4:5], s[100:101]
	v_exp_f32_e32 v244, v244
	v_exp_f32_e32 v245, v245
	v_pk_mul_f32 v[4:5], v[84:85], v[4:5]
	v_pk_add_f32 v[244:245], v[244:245], s[98:99]
	v_rcp_f32_e32 v28, v244
	v_rcp_f32_e32 v29, v245
	v_pk_mul_f32 v[244:245], v[2:3], s[100:101]
	v_exp_f32_e32 v244, v244
	v_exp_f32_e32 v245, v245
	v_pk_mul_f32 v[2:3], v[82:83], v[2:3]
	v_pk_add_f32 v[244:245], v[244:245], s[98:99]
	v_rcp_f32_e32 v26, v244
	v_rcp_f32_e32 v27, v245
	v_pk_mul_f32 v[4:5], v[4:5], v[28:29]
	v_pk_mul_f32 v[2:3], v[2:3], v[26:27]
	v_pk_fma_f32 v[26:27], v[8:9], v[98:99], v[22:23]
	s_nop 0
	v_fmac_f32_dpp v26, v8, v58 row_shr:1 row_mask:0xf bank_mask:0xf
	v_fmac_f32_dpp v27, v9, v59 row_shr:1 row_mask:0xf bank_mask:0xf
	v_fmac_f32_dpp v26, v8, v54 row_shr:2 row_mask:0xf bank_mask:0xf
	v_fma_f32 v8, v6, v100, v24
	v_fmac_f32_dpp v26, v108, v58 row_shl:15 row_mask:0xf bank_mask:0xf
	v_fmac_f32_dpp v27, v9, v55 row_shr:2 row_mask:0xf bank_mask:0xf
	v_fmac_f32_dpp v26, v108, v54 row_shl:14 row_mask:0xf bank_mask:0xf
	v_fmac_f32_dpp v27, v109, v59 row_shl:15 row_mask:0xf bank_mask:0xf
	v_fmac_f32_dpp v8, v6, v60 row_shr:1 row_mask:0xf bank_mask:0xf
	v_fmac_f32_dpp v27, v109, v55 row_shl:14 row_mask:0xf bank_mask:0xf
	v_fma_f32 v9, v7, v101, v25
	v_fmac_f32_dpp v8, v6, v56 row_shr:2 row_mask:0xf bank_mask:0xf
	v_fmac_f32_dpp v9, v7, v61 row_shr:1 row_mask:0xf bank_mask:0xf
	v_fmac_f32_dpp v8, v106, v60 row_shl:15 row_mask:0xf bank_mask:0xf
	v_fmac_f32_dpp v9, v7, v57 row_shr:2 row_mask:0xf bank_mask:0xf
	v_fmac_f32_dpp v8, v106, v56 row_shl:14 row_mask:0xf bank_mask:0xf
	v_fmac_f32_dpp v9, v107, v61 row_shl:15 row_mask:0xf bank_mask:0xf
	v_pk_mul_f32 v[18:19], v[18:19], v[26:27]
	v_fmac_f32_dpp v9, v107, v57 row_shl:14 row_mask:0xf bank_mask:0xf
	v_pk_mul_f32 v[244:245], v[8:9], s[100:101]
	v_exp_f32_e32 v244, v244
	v_exp_f32_e32 v245, v245
	v_pk_mul_f32 v[8:9], v[20:21], v[8:9]
	v_pk_add_f32 v[244:245], v[244:245], s[98:99]
	v_rcp_f32_e32 v28, v244
	v_rcp_f32_e32 v29, v245
	v_pk_mul_f32 v[244:245], v[26:27], s[100:101]
	v_exp_f32_e32 v244, v244
	v_exp_f32_e32 v245, v245
	v_pk_mul_f32 v[8:9], v[8:9], v[28:29]
	v_pk_add_f32 v[244:245], v[244:245], s[98:99]
	v_rcp_f32_e32 v6, v244
	v_rcp_f32_e32 v7, v245
	v_pk_fma_f32 v[20:21], v[106:107], v[100:101], v[24:25]
	v_pk_mul_f32 v[6:7], v[18:19], v[6:7]
	v_pk_fma_f32 v[18:19], v[108:109], v[98:99], v[22:23]
	v_pk_fma_f32 v[24:25], v[12:13], v[100:101], v[24:25]
	v_fmac_f32_dpp v18, v108, v58 row_shr:1 row_mask:0xf bank_mask:0xf
	v_fmac_f32_dpp v19, v109, v59 row_shr:1 row_mask:0xf bank_mask:0xf
	v_fmac_f32_dpp v18, v108, v54 row_shr:2 row_mask:0xf bank_mask:0xf
	v_fmac_f32_dpp v19, v109, v55 row_shr:2 row_mask:0xf bank_mask:0xf
	v_fmac_f32_dpp v18, v10, v58 row_shl:15 row_mask:0xf bank_mask:0xf
	v_fmac_f32_dpp v19, v11, v59 row_shl:15 row_mask:0xf bank_mask:0xf
	v_fmac_f32_dpp v18, v10, v54 row_shl:14 row_mask:0xf bank_mask:0xf
	v_fmac_f32_dpp v19, v11, v55 row_shl:14 row_mask:0xf bank_mask:0xf
	v_fmac_f32_dpp v20, v106, v60 row_shr:1 row_mask:0xf bank_mask:0xf
	v_fmac_f32_dpp v21, v107, v61 row_shr:1 row_mask:0xf bank_mask:0xf
	v_fmac_f32_dpp v20, v106, v56 row_shr:2 row_mask:0xf bank_mask:0xf
	v_fmac_f32_dpp v21, v107, v57 row_shr:2 row_mask:0xf bank_mask:0xf
	v_fmac_f32_dpp v20, v12, v60 row_shl:15 row_mask:0xf bank_mask:0xf
	v_fmac_f32_dpp v21, v13, v61 row_shl:15 row_mask:0xf bank_mask:0xf
	v_fmac_f32_dpp v20, v12, v56 row_shl:14 row_mask:0xf bank_mask:0xf
	v_fmac_f32_dpp v21, v13, v57 row_shl:14 row_mask:0xf bank_mask:0xf
	v_pk_mul_f32 v[244:245], v[20:21], s[100:101]
	v_exp_f32_e32 v244, v244
	v_exp_f32_e32 v245, v245
	v_pk_mul_f32 v[16:17], v[16:17], v[20:21]
	v_pk_add_f32 v[244:245], v[244:245], s[98:99]
	v_rcp_f32_e32 v28, v244
	v_rcp_f32_e32 v29, v245
	v_pk_mul_f32 v[244:245], v[18:19], s[100:101]
	v_exp_f32_e32 v244, v244
	v_exp_f32_e32 v245, v245
	v_pk_mul_f32 v[14:15], v[14:15], v[18:19]
	v_pk_add_f32 v[244:245], v[244:245], s[98:99]
	v_rcp_f32_e32 v26, v244
	v_rcp_f32_e32 v27, v245
	v_pk_mul_f32 v[16:17], v[16:17], v[28:29]
	v_pk_mul_f32 v[14:15], v[14:15], v[26:27]
	v_pk_fma_f32 v[18:19], v[10:11], v[98:99], v[22:23]
	v_mov_b64_e32 v[22:23], s[66:67]
	v_fmac_f32_dpp v18, v10, v58 row_shr:1 row_mask:0xf bank_mask:0xf
	s_nop 0
	v_fmac_f32_dpp v18, v10, v54 row_shr:2 row_mask:0xf bank_mask:0xf
	s_nop 0
	v_fmac_f32_dpp v18, v74, v58 row_shl:15 row_mask:0xf bank_mask:0xf
	s_ashr_i32 s47, s46, 31
	v_fmac_f32_dpp v18, v74, v54 row_shl:14 row_mask:0xf bank_mask:0xf
	v_fmac_f32_dpp v19, v11, v59 row_shr:1 row_mask:0xf bank_mask:0xf
	s_andn2_b64 vcc, exec, s[4:5]
	v_fmac_f32_dpp v19, v11, v55 row_shr:2 row_mask:0xf bank_mask:0xf
	v_fmac_f32_dpp v24, v12, v60 row_shr:1 row_mask:0xf bank_mask:0xf
	v_fmac_f32_dpp v19, v75, v59 row_shl:15 row_mask:0xf bank_mask:0xf
	s_nop 0
	v_fmac_f32_dpp v19, v75, v55 row_shl:14 row_mask:0xf bank_mask:0xf
	s_mov_b64 s[4:5], -1
	v_fmac_f32_dpp v24, v12, v56 row_shr:2 row_mask:0xf bank_mask:0xf
	v_fmac_f32_dpp v25, v13, v61 row_shr:1 row_mask:0xf bank_mask:0xf
	v_fmac_f32_dpp v24, v76, v60 row_shl:15 row_mask:0xf bank_mask:0xf
	v_fmac_f32_dpp v25, v13, v57 row_shr:2 row_mask:0xf bank_mask:0xf
	v_fmac_f32_dpp v24, v76, v56 row_shl:14 row_mask:0xf bank_mask:0xf
	v_fmac_f32_dpp v25, v77, v61 row_shl:15 row_mask:0xf bank_mask:0xf
	v_lshl_add_u32 v1, s28, 8, v185
	v_fmac_f32_dpp v25, v77, v57 row_shl:14 row_mask:0xf bank_mask:0xf
	v_pk_mul_f32 v[244:245], v[24:25], s[100:101]
	v_exp_f32_e32 v244, v244
	v_exp_f32_e32 v245, v245
	v_pk_mul_f32 v[20:21], v[72:73], v[24:25]
	v_pk_add_f32 v[244:245], v[244:245], s[98:99]
	v_rcp_f32_e32 v12, v244
	v_rcp_f32_e32 v13, v245
	v_pk_mul_f32 v[244:245], v[18:19], s[100:101]
	v_exp_f32_e32 v244, v244
	v_exp_f32_e32 v245, v245
	s_nop 0
	v_pk_add_f32 v[244:245], v[244:245], s[98:99]
	v_rcp_f32_e32 v10, v244
	v_rcp_f32_e32 v11, v245
	v_mad_i64_i32 v[24:25], s[28:29], v1, s12, v[22:23]
	s_lshl_b64 s[28:29], s[46:47], 1
	v_pk_mul_f32 v[18:19], v[70:71], v[18:19]
	v_lshl_add_u64 v[24:25], v[24:25], 0, s[28:29]
	v_pk_mul_f32 v[12:13], v[20:21], v[12:13]
	v_pk_mul_f32 v[10:11], v[18:19], v[10:11]
	v_lshl_add_u64 v[24:25], v[24:25], 0, v[182:183]
	v_cvt_pk_bf16_f32 v18, v78, v79
	v_cvt_pk_bf16_f32 v19, v80, v81
	v_cvt_pk_bf16_f32 v20, v66, v67
	v_cvt_pk_bf16_f32 v21, v68, v69
	global_store_dwordx4 v[24:25], v[18:21], off
	v_or_b32_e32 v24, 16, v1
	v_mad_i64_i32 v[24:25], s[46:47], v24, s12, v[22:23]
	v_lshl_add_u64 v[24:25], v[24:25], 0, s[28:29]
	v_lshl_add_u64 v[24:25], v[24:25], 0, v[182:183]
	v_cvt_pk_bf16_f32 v18, v62, v63
	v_cvt_pk_bf16_f32 v19, v64, v65
	v_cvt_pk_bf16_f32 v20, v42, v43
	v_cvt_pk_bf16_f32 v21, v44, v45
	global_store_dwordx4 v[24:25], v[18:21], off
	v_or_b32_e32 v24, 32, v1
	v_mad_i64_i32 v[24:25], s[46:47], v24, s12, v[22:23]
	v_lshl_add_u64 v[24:25], v[24:25], 0, s[28:29]
	v_lshl_add_u64 v[24:25], v[24:25], 0, v[182:183]
	v_cvt_pk_bf16_f32 v18, v50, v51
	v_cvt_pk_bf16_f32 v19, v52, v53
	v_cvt_pk_bf16_f32 v20, v38, v39
	v_cvt_pk_bf16_f32 v21, v40, v41
	global_store_dwordx4 v[24:25], v[18:21], off
	v_or_b32_e32 v24, 48, v1
	v_mad_i64_i32 v[24:25], s[46:47], v24, s12, v[22:23]
	v_lshl_add_u64 v[24:25], v[24:25], 0, s[28:29]
	v_lshl_add_u64 v[24:25], v[24:25], 0, v[182:183]
	v_cvt_pk_bf16_f32 v18, v46, v47
	v_cvt_pk_bf16_f32 v19, v48, v49
	v_cvt_pk_bf16_f32 v20, v34, v35
	v_cvt_pk_bf16_f32 v21, v36, v37
	global_store_dwordx4 v[24:25], v[18:21], off
	v_add_u32_e32 v24, 0x80, v1
	s_nop 0
	v_cvt_pk_bf16_f32 v18, v102, v103
	v_cvt_pk_bf16_f32 v19, v104, v105
	v_cvt_pk_bf16_f32 v20, v10, v11
	v_mad_i64_i32 v[10:11], s[46:47], v24, s12, v[22:23]
	v_lshl_add_u64 v[10:11], v[10:11], 0, s[28:29]
	v_lshl_add_u64 v[10:11], v[10:11], 0, v[182:183]
	v_cvt_pk_bf16_f32 v21, v12, v13
	global_store_dwordx4 v[10:11], v[18:21], off
	v_cvt_pk_bf16_f32 v10, v94, v95
	v_cvt_pk_bf16_f32 v11, v96, v97
	v_cvt_pk_bf16_f32 v12, v14, v15
	v_add_u32_e32 v14, 0x90, v1
	v_mad_i64_i32 v[14:15], s[46:47], v14, s12, v[22:23]
	v_lshl_add_u64 v[14:15], v[14:15], 0, s[28:29]
	v_lshl_add_u64 v[14:15], v[14:15], 0, v[182:183]
	v_cvt_pk_bf16_f32 v13, v16, v17
	global_store_dwordx4 v[14:15], v[10:13], off
	s_nop 1
	v_cvt_pk_bf16_f32 v10, v90, v91
	v_cvt_pk_bf16_f32 v11, v92, v93
	v_cvt_pk_bf16_f32 v12, v6, v7
	v_add_u32_e32 v6, 0xa0, v1
	v_mad_i64_i32 v[6:7], s[46:47], v6, s12, v[22:23]
	v_lshl_add_u64 v[6:7], v[6:7], 0, s[28:29]
	v_lshl_add_u64 v[6:7], v[6:7], 0, v[182:183]
	v_add_u32_e32 v1, 0xb0, v1
	v_cvt_pk_bf16_f32 v13, v8, v9
	global_store_dwordx4 v[6:7], v[10:13], off
	v_cvt_pk_bf16_f32 v6, v86, v87
	v_cvt_pk_bf16_f32 v7, v88, v89
	v_cvt_pk_bf16_f32 v8, v2, v3
	v_mad_i64_i32 v[2:3], s[46:47], v1, s12, v[22:23]
	v_lshl_add_u64 v[2:3], v[2:3], 0, s[28:29]
	v_lshl_add_u64 v[2:3], v[2:3], 0, v[182:183]
	v_cvt_pk_bf16_f32 v9, v4, v5
	global_store_dwordx4 v[2:3], v[6:9], off
	s_cbranch_vccnz .LBB0_553
	s_andn2_b64 vcc, exec, s[16:17]
	s_mov_b32 s3, s40
	s_mov_b64 s[28:29], s[94:95]
	s_mov_b64 s[4:5], s[36:37]
	s_cbranch_vccnz .LBB0_590
	s_ashr_i32 s3, s40, 5
	s_mul_hi_i32 s4, s3, 0x5800
	s_mulk_i32 s3, 0x5800
	v_readlane_b32 s5, v255, 14
	s_add_u32 s28, s5, s3
	v_readlane_b32 s3, v255, 15
	s_addc_u32 s29, s3, s4
	s_mov_b32 s3, s38
	s_mov_b64 s[4:5], s[62:63]

.LBB0_1323:
	s_or_b64 exec, exec, s[52:53]
	s_waitcnt lgkmcnt(0)
	s_barrier
	ds_read_b128 v[150:153], v223 offset:512
	ds_read_b128 v[154:157], v223 offset:1536
	ds_read_b128 v[162:165], v223 offset:2560
	ds_read_b128 v[138:141], v223 offset:3584
	v_mov_b32_e32 v158, 0
	v_mov_b32_e32 v159, 0
	v_mov_b32_e32 v160, 0
	v_mov_b32_e32 v161, 0
	s_and_saveexec_b64 s[52:53], s[36:37]
	v_add_u32_e32 v147, s77, v215
	ds_read_b128 v[158:161], v147 offset:512
	s_or_b64 exec, exec, s[52:53]
	v_fmamk_f32 v146, v146, 0x3a800000, v222
	v_rsq_f32_e32 v200, v146
	s_waitcnt lgkmcnt(0)
	v_fma_f32 v146, v166, v162, v138
	v_lshl_add_u32 v147, s30, 1, v1
	s_nop 4
	v_fmac_f32_dpp v146, v166, v154 row_shr:1 row_mask:0xf bank_mask:0xf
	v_mad_i64_i32 v[208:209], s[52:53], v147, s65, 0
	v_fmamk_f32 v147, v149, 0x3a800000, v222
	v_fmac_f32_dpp v146, v166, v150 row_shr:2 row_mask:0xf bank_mask:0xf
	v_rsq_f32_e32 v198, v147
	v_pk_fma_f32 v[78:79], v[78:79], v[200:201], v[122:123] op_sel_hi:[1,0,1]
	v_fma_f32 v147, v167, v163, v139
	v_fmamk_f32 v148, v148, 0x3a800000, v222
	v_fmac_f32_dpp v146, v78, v154 row_shl:15 row_mask:0xf bank_mask:0xf
	v_fmac_f32_dpp v147, v167, v155 row_shr:1 row_mask:0xf bank_mask:0xf
	v_fmac_f32_dpp v146, v78, v150 row_shl:14 row_mask:0xf bank_mask:0xf
	v_rsq_f32_e32 v196, v148
	v_fmac_f32_dpp v147, v167, v151 row_shr:2 row_mask:0xf bank_mask:0xf
	v_pk_fma_f32 v[148:149], v[168:169], v[164:165], v[140:141]
	v_fmac_f32_dpp v147, v79, v155 row_shl:15 row_mask:0xf bank_mask:0xf
	v_pk_fma_f32 v[80:81], v[80:81], v[200:201], v[124:125] op_sel_hi:[1,0,1]
	v_fmac_f32_dpp v147, v79, v151 row_shl:14 row_mask:0xf bank_mask:0xf
	v_fmac_f32_dpp v148, v168, v156 row_shr:1 row_mask:0xf bank_mask:0xf
	v_pk_fma_f32 v[224:225], v[130:131], v[198:199], v[122:123] op_sel_hi:[1,0,1]
	v_fmac_f32_dpp v148, v168, v152 row_shr:2 row_mask:0xf bank_mask:0xf
	v_pk_fma_f32 v[130:131], v[78:79], v[162:163], v[138:139]
	v_fmac_f32_dpp v148, v80, v156 row_shl:15 row_mask:0xf bank_mask:0xf
	v_fmac_f32_dpp v149, v169, v157 row_shr:1 row_mask:0xf bank_mask:0xf
	v_fmac_f32_dpp v148, v80, v152 row_shl:14 row_mask:0xf bank_mask:0xf
	v_fmac_f32_dpp v149, v169, v153 row_shr:2 row_mask:0xf bank_mask:0xf
	v_pk_fma_f32 v[210:211], v[132:133], v[198:199], v[124:125] op_sel_hi:[1,0,1]
	v_fmac_f32_dpp v149, v81, v157 row_shl:15 row_mask:0xf bank_mask:0xf
	v_pk_fma_f32 v[132:133], v[80:81], v[164:165], v[140:141]
	v_fmac_f32_dpp v149, v81, v153 row_shl:14 row_mask:0xf bank_mask:0xf
	v_fmac_f32_dpp v130, v78, v154 row_shr:1 row_mask:0xf bank_mask:0xf
	v_pk_fma_f32 v[134:135], v[134:135], v[196:197], v[122:123] op_sel_hi:[1,0,1]
	v_fmac_f32_dpp v130, v78, v150 row_shr:2 row_mask:0xf bank_mask:0xf
	v_fma_f32 v78, v224, v162, v138
	v_fmac_f32_dpp v130, v224, v154 row_shl:15 row_mask:0xf bank_mask:0xf
	v_pk_fma_f32 v[136:137], v[136:137], v[196:197], v[124:125] op_sel_hi:[1,0,1]
	v_fmac_f32_dpp v130, v224, v150 row_shl:14 row_mask:0xf bank_mask:0xf
	v_fmac_f32_dpp v131, v79, v155 row_shr:1 row_mask:0xf bank_mask:0xf
	v_fmac_f32_dpp v132, v80, v156 row_shr:1 row_mask:0xf bank_mask:0xf
	v_fmac_f32_dpp v131, v79, v151 row_shr:2 row_mask:0xf bank_mask:0xf
	v_fma_f32 v79, v225, v163, v139
	v_fmac_f32_dpp v131, v225, v155 row_shl:15 row_mask:0xf bank_mask:0xf
	v_pk_fma_f32 v[138:139], v[134:135], v[162:163], v[138:139]
	v_fmac_f32_dpp v131, v225, v151 row_shl:14 row_mask:0xf bank_mask:0xf
	s_lshl_b32 s50, s50, 7
	v_fmac_f32_dpp v132, v80, v152 row_shr:2 row_mask:0xf bank_mask:0xf
	v_fma_f32 v80, v210, v164, v140
	v_fmac_f32_dpp v132, v210, v156 row_shl:15 row_mask:0xf bank_mask:0xf
	v_fmac_f32_dpp v133, v81, v157 row_shr:1 row_mask:0xf bank_mask:0xf
	v_fmac_f32_dpp v132, v210, v152 row_shl:14 row_mask:0xf bank_mask:0xf
	v_or_b32_e32 v202, s50, v186
	v_fmac_f32_dpp v133, v81, v153 row_shr:2 row_mask:0xf bank_mask:0xf
	v_fma_f32 v81, v211, v165, v141
	v_fmac_f32_dpp v133, v211, v157 row_shl:15 row_mask:0xf bank_mask:0xf
	v_pk_fma_f32 v[140:141], v[136:137], v[164:165], v[140:141]
	v_fmac_f32_dpp v133, v211, v153 row_shl:14 row_mask:0xf bank_mask:0xf
	v_ashrrev_i32_e32 v203, 31, v202
	v_fmac_f32_dpp v78, v224, v154 row_shr:1 row_mask:0xf bank_mask:0xf
	v_lshl_add_u64 v[168:169], s[28:29], 0, v[208:209]
	v_fmac_f32_dpp v78, v224, v150 row_shr:2 row_mask:0xf bank_mask:0xf
	v_lshl_add_u64 v[166:167], v[202:203], 2, v[168:169]
	v_fmac_f32_dpp v78, v134, v154 row_shl:15 row_mask:0xf bank_mask:0xf
	v_fmac_f32_dpp v79, v225, v155 row_shr:1 row_mask:0xf bank_mask:0xf
	v_fmac_f32_dpp v78, v134, v150 row_shl:14 row_mask:0xf bank_mask:0xf
	v_fmac_f32_dpp v79, v225, v151 row_shr:2 row_mask:0xf bank_mask:0xf
	v_fmac_f32_dpp v80, v210, v156 row_shr:1 row_mask:0xf bank_mask:0xf
	v_fmac_f32_dpp v79, v135, v155 row_shl:15 row_mask:0xf bank_mask:0xf
	v_fmac_f32_dpp v80, v210, v152 row_shr:2 row_mask:0xf bank_mask:0xf
	v_fmac_f32_dpp v79, v135, v151 row_shl:14 row_mask:0xf bank_mask:0xf
	v_fmac_f32_dpp v80, v136, v156 row_shl:15 row_mask:0xf bank_mask:0xf
	v_fmac_f32_dpp v81, v211, v157 row_shr:1 row_mask:0xf bank_mask:0xf
	v_fmac_f32_dpp v80, v136, v152 row_shl:14 row_mask:0xf bank_mask:0xf
	v_fmac_f32_dpp v81, v211, v153 row_shr:2 row_mask:0xf bank_mask:0xf
	v_fmac_f32_dpp v138, v134, v154 row_shr:1 row_mask:0xf bank_mask:0xf
	v_fmac_f32_dpp v81, v137, v157 row_shl:15 row_mask:0xf bank_mask:0xf
	v_fmac_f32_dpp v138, v134, v150 row_shr:2 row_mask:0xf bank_mask:0xf
	v_fmac_f32_dpp v81, v137, v153 row_shl:14 row_mask:0xf bank_mask:0xf
	v_fmac_f32_dpp v138, v158, v154 row_shl:15 row_mask:0xf bank_mask:0xf
	v_fmac_f32_dpp v139, v135, v155 row_shr:1 row_mask:0xf bank_mask:0xf
	v_fmac_f32_dpp v138, v158, v150 row_shl:14 row_mask:0xf bank_mask:0xf
	v_fmac_f32_dpp v139, v135, v151 row_shr:2 row_mask:0xf bank_mask:0xf
	v_fmac_f32_dpp v140, v136, v156 row_shr:1 row_mask:0xf bank_mask:0xf
	v_fmac_f32_dpp v139, v159, v155 row_shl:15 row_mask:0xf bank_mask:0xf
	v_fmac_f32_dpp v140, v136, v152 row_shr:2 row_mask:0xf bank_mask:0xf
	v_fmac_f32_dpp v139, v159, v151 row_shl:14 row_mask:0xf bank_mask:0xf
	v_fmac_f32_dpp v140, v160, v156 row_shl:15 row_mask:0xf bank_mask:0xf
	v_fmac_f32_dpp v141, v137, v157 row_shr:1 row_mask:0xf bank_mask:0xf
	v_fmac_f32_dpp v140, v160, v152 row_shl:14 row_mask:0xf bank_mask:0xf
	v_fmac_f32_dpp v141, v137, v153 row_shr:2 row_mask:0xf bank_mask:0xf
	s_nop 0
	v_fmac_f32_dpp v141, v161, v157 row_shl:15 row_mask:0xf bank_mask:0xf
	s_nop 0
	v_fmac_f32_dpp v141, v161, v153 row_shl:14 row_mask:0xf bank_mask:0xf
	s_and_saveexec_b64 s[52:53], s[38:39]
	s_cbranch_execz .LBB0_1327
	v_add_co_u32_e32 v134, vcc, 0x2000, v166
	s_nop 1
	v_addc_co_u32_e32 v135, vcc, 0, v167, vcc
	global_store_dwordx4 v[134:135], v[138:141], off offset:3072
.LBB0_1327:
	s_or_b64 exec, exec, s[52:53]
	ds_read_b128 v[150:153], v223
	ds_read_b128 v[154:157], v223 offset:1024
	ds_read_b128 v[162:165], v223 offset:2048
	ds_read_b128 v[134:137], v223 offset:3072
	v_mov_b32_e32 v158, 0
	v_mov_b32_e32 v159, 0
	v_mov_b32_e32 v160, 0
	v_mov_b32_e32 v161, 0
	s_and_saveexec_b64 s[52:53], s[36:37]
	v_add_u32_e32 v158, 0, v215
	v_add_u32_e32 v158, 0x20000, v158
	ds_read_b128 v[158:161], v158
	s_or_b64 exec, exec, s[52:53]
	v_mov_b32_e32 v197, v196
	v_mov_b32_e32 v201, v200
	v_pk_fma_f32 v[210:211], v[62:63], v[196:197], v[118:119] op_sel_hi:[1,0,1]
	v_pk_fma_f32 v[62:63], v[52:53], v[198:199], v[120:121] op_sel_hi:[1,0,1]
	v_pk_fma_f32 v[52:53], v[46:47], v[200:201], v[118:119] op_sel_hi:[1,0,1]
	s_waitcnt lgkmcnt(0)
	v_pk_fma_f32 v[46:47], v[142:143], v[162:163], v[134:135]
	s_nop 4
	v_fmac_f32_dpp v46, v142, v154 row_shr:1 row_mask:0xf bank_mask:0xf
	v_mov_b32_e32 v199, v198
	v_fmac_f32_dpp v46, v142, v150 row_shr:2 row_mask:0xf bank_mask:0xf
	v_fmac_f32_dpp v47, v143, v155 row_shr:1 row_mask:0xf bank_mask:0xf
	v_fmac_f32_dpp v46, v52, v154 row_shl:15 row_mask:0xf bank_mask:0xf
	v_pk_fma_f32 v[208:209], v[64:65], v[196:197], v[120:121] op_sel_hi:[1,0,1]
	v_fmac_f32_dpp v46, v52, v150 row_shl:14 row_mask:0xf bank_mask:0xf
	v_pk_fma_f32 v[64:65], v[50:51], v[198:199], v[118:119] op_sel_hi:[1,0,1]
	v_fmac_f32_dpp v47, v143, v151 row_shr:2 row_mask:0xf bank_mask:0xf
	v_pk_fma_f32 v[50:51], v[48:49], v[200:201], v[120:121] op_sel_hi:[1,0,1]
	v_fmac_f32_dpp v47, v53, v155 row_shl:15 row_mask:0xf bank_mask:0xf
	v_pk_fma_f32 v[48:49], v[144:145], v[164:165], v[136:137]
	v_fmac_f32_dpp v47, v53, v151 row_shl:14 row_mask:0xf bank_mask:0xf
	v_fmac_f32_dpp v48, v144, v156 row_shr:1 row_mask:0xf bank_mask:0xf
	v_fmac_f32_dpp v49, v145, v157 row_shr:1 row_mask:0xf bank_mask:0xf
	v_fmac_f32_dpp v48, v144, v152 row_shr:2 row_mask:0xf bank_mask:0xf
	v_fmac_f32_dpp v49, v145, v153 row_shr:2 row_mask:0xf bank_mask:0xf
	v_fmac_f32_dpp v48, v50, v156 row_shl:15 row_mask:0xf bank_mask:0xf
	v_fmac_f32_dpp v49, v51, v157 row_shl:15 row_mask:0xf bank_mask:0xf
	v_fmac_f32_dpp v48, v50, v152 row_shl:14 row_mask:0xf bank_mask:0xf
	v_fmac_f32_dpp v49, v51, v153 row_shl:14 row_mask:0xf bank_mask:0xf
	v_pk_mul_f32 v[244:245], v[48:49], s[100:101]
	v_exp_f32_e32 v244, v244
	v_exp_f32_e32 v245, v245
	v_pk_mul_f32 v[48:49], v[148:149], v[48:49]
	v_pk_add_f32 v[244:245], v[244:245], s[98:99]
	v_rcp_f32_e32 v144, v244
	v_rcp_f32_e32 v145, v245
	v_pk_mul_f32 v[244:245], v[46:47], s[100:101]
	v_exp_f32_e32 v244, v244
	v_exp_f32_e32 v245, v245
	v_pk_mul_f32 v[46:47], v[146:147], v[46:47]
	v_pk_add_f32 v[244:245], v[244:245], s[98:99]
	v_rcp_f32_e32 v142, v244
	v_rcp_f32_e32 v143, v245
	v_pk_mul_f32 v[48:49], v[48:49], v[144:145]
	v_pk_mul_f32 v[46:47], v[46:47], v[142:143]
	v_pk_fma_f32 v[142:143], v[52:53], v[162:163], v[134:135]
	s_nop 0
	v_fmac_f32_dpp v142, v52, v154 row_shr:1 row_mask:0xf bank_mask:0xf
	v_fmac_f32_dpp v143, v53, v155 row_shr:1 row_mask:0xf bank_mask:0xf
	v_fmac_f32_dpp v142, v52, v150 row_shr:2 row_mask:0xf bank_mask:0xf
	v_fmac_f32_dpp v143, v53, v151 row_shr:2 row_mask:0xf bank_mask:0xf
	v_fmac_f32_dpp v142, v64, v154 row_shl:15 row_mask:0xf bank_mask:0xf
	v_pk_fma_f32 v[52:53], v[50:51], v[164:165], v[136:137]
	v_fmac_f32_dpp v142, v64, v150 row_shl:14 row_mask:0xf bank_mask:0xf
	v_fmac_f32_dpp v143, v65, v155 row_shl:15 row_mask:0xf bank_mask:0xf
	v_fmac_f32_dpp v52, v50, v156 row_shr:1 row_mask:0xf bank_mask:0xf
	v_fmac_f32_dpp v143, v65, v151 row_shl:14 row_mask:0xf bank_mask:0xf
	v_fmac_f32_dpp v52, v50, v152 row_shr:2 row_mask:0xf bank_mask:0xf
	v_fmac_f32_dpp v53, v51, v157 row_shr:1 row_mask:0xf bank_mask:0xf
	v_fmac_f32_dpp v52, v62, v156 row_shl:15 row_mask:0xf bank_mask:0xf
	v_pk_mul_f32 v[130:131], v[130:131], v[142:143]
	v_fmac_f32_dpp v52, v62, v152 row_shl:14 row_mask:0xf bank_mask:0xf
	v_fmac_f32_dpp v53, v51, v153 row_shr:2 row_mask:0xf bank_mask:0xf
	s_nop 0
	v_fmac_f32_dpp v53, v63, v157 row_shl:15 row_mask:0xf bank_mask:0xf
	s_nop 0
	v_fmac_f32_dpp v53, v63, v153 row_shl:14 row_mask:0xf bank_mask:0xf
	v_pk_mul_f32 v[244:245], v[52:53], s[100:101]
	v_exp_f32_e32 v244, v244
	v_exp_f32_e32 v245, v245
	v_pk_mul_f32 v[52:53], v[132:133], v[52:53]
	v_pk_add_f32 v[244:245], v[244:245], s[98:99]
	v_rcp_f32_e32 v144, v244
	v_rcp_f32_e32 v145, v245
	v_pk_mul_f32 v[244:245], v[142:143], s[100:101]
	v_exp_f32_e32 v244, v244
	v_exp_f32_e32 v245, v245
	v_pk_mul_f32 v[52:53], v[52:53], v[144:145]
	v_pk_add_f32 v[244:245], v[244:245], s[98:99]
	v_rcp_f32_e32 v50, v244
	v_rcp_f32_e32 v51, v245
	s_nop 0
	v_pk_mul_f32 v[50:51], v[130:131], v[50:51]
	v_pk_fma_f32 v[130:131], v[64:65], v[162:163], v[134:135]
	v_pk_fma_f32 v[134:135], v[210:211], v[162:163], v[134:135]
	v_fmac_f32_dpp v130, v64, v154 row_shr:1 row_mask:0xf bank_mask:0xf
	v_fmac_f32_dpp v131, v65, v155 row_shr:1 row_mask:0xf bank_mask:0xf
	v_fmac_f32_dpp v130, v64, v150 row_shr:2 row_mask:0xf bank_mask:0xf
	v_fmac_f32_dpp v131, v65, v151 row_shr:2 row_mask:0xf bank_mask:0xf
	v_fmac_f32_dpp v130, v210, v154 row_shl:15 row_mask:0xf bank_mask:0xf
	v_pk_fma_f32 v[64:65], v[62:63], v[164:165], v[136:137]
	v_fmac_f32_dpp v130, v210, v150 row_shl:14 row_mask:0xf bank_mask:0xf
	v_fmac_f32_dpp v131, v211, v155 row_shl:15 row_mask:0xf bank_mask:0xf
	v_pk_fma_f32 v[136:137], v[208:209], v[164:165], v[136:137]
	v_fmac_f32_dpp v131, v211, v151 row_shl:14 row_mask:0xf bank_mask:0xf
	v_fmac_f32_dpp v64, v62, v156 row_shr:1 row_mask:0xf bank_mask:0xf
	v_fmac_f32_dpp v65, v63, v157 row_shr:1 row_mask:0xf bank_mask:0xf
	v_fmac_f32_dpp v64, v62, v152 row_shr:2 row_mask:0xf bank_mask:0xf
	v_pk_mul_f32 v[78:79], v[78:79], v[130:131]
	v_fmac_f32_dpp v64, v208, v156 row_shl:15 row_mask:0xf bank_mask:0xf
	v_fmac_f32_dpp v65, v63, v153 row_shr:2 row_mask:0xf bank_mask:0xf
	v_fmac_f32_dpp v64, v208, v152 row_shl:14 row_mask:0xf bank_mask:0xf
	v_fmac_f32_dpp v65, v209, v157 row_shl:15 row_mask:0xf bank_mask:0xf
	v_fmac_f32_dpp v134, v210, v154 row_shr:1 row_mask:0xf bank_mask:0xf
	v_fmac_f32_dpp v65, v209, v153 row_shl:14 row_mask:0xf bank_mask:0xf
	v_pk_mul_f32 v[244:245], v[64:65], s[100:101]
	v_exp_f32_e32 v244, v244
	v_exp_f32_e32 v245, v245
	v_pk_mul_f32 v[64:65], v[80:81], v[64:65]
	v_pk_add_f32 v[244:245], v[244:245], s[98:99]
	v_rcp_f32_e32 v132, v244
	v_rcp_f32_e32 v133, v245
	v_pk_mul_f32 v[244:245], v[130:131], s[100:101]
	v_exp_f32_e32 v244, v244
	v_exp_f32_e32 v245, v245
	v_pk_mul_f32 v[64:65], v[64:65], v[132:133]
	v_pk_add_f32 v[244:245], v[244:245], s[98:99]
	v_rcp_f32_e32 v62, v244
	v_rcp_f32_e32 v63, v245
	v_fmac_f32_dpp v134, v210, v150 row_shr:2 row_mask:0xf bank_mask:0xf
	v_pk_mul_f32 v[62:63], v[78:79], v[62:63]
	v_fmac_f32_dpp v134, v158, v154 row_shl:15 row_mask:0xf bank_mask:0xf
	v_fmac_f32_dpp v135, v211, v155 row_shr:1 row_mask:0xf bank_mask:0xf
	v_fmac_f32_dpp v134, v158, v150 row_shl:14 row_mask:0xf bank_mask:0xf
	v_fmac_f32_dpp v135, v211, v151 row_shr:2 row_mask:0xf bank_mask:0xf
	v_fmac_f32_dpp v136, v208, v156 row_shr:1 row_mask:0xf bank_mask:0xf
	v_fmac_f32_dpp v135, v159, v155 row_shl:15 row_mask:0xf bank_mask:0xf
	v_fmac_f32_dpp v136, v208, v152 row_shr:2 row_mask:0xf bank_mask:0xf
	v_fmac_f32_dpp v135, v159, v151 row_shl:14 row_mask:0xf bank_mask:0xf
	v_fmac_f32_dpp v136, v160, v156 row_shl:15 row_mask:0xf bank_mask:0xf
	v_fmac_f32_dpp v137, v209, v157 row_shr:1 row_mask:0xf bank_mask:0xf
	v_fmac_f32_dpp v136, v160, v152 row_shl:14 row_mask:0xf bank_mask:0xf
	v_fmac_f32_dpp v137, v209, v153 row_shr:2 row_mask:0xf bank_mask:0xf
	s_nop 0
	v_fmac_f32_dpp v137, v161, v157 row_shl:15 row_mask:0xf bank_mask:0xf
	s_nop 0
	v_fmac_f32_dpp v137, v161, v153 row_shl:14 row_mask:0xf bank_mask:0xf
	s_and_saveexec_b64 s[52:53], s[38:39]
	s_cbranch_execz .LBB0_1331
	global_store_dwordx4 v[166:167], v[134:137], off
.LBB0_1331:
	s_or_b64 exec, exec, s[52:53]
	v_pk_mul_f32 v[244:245], v[136:137], s[100:101]
	v_exp_f32_e32 v244, v244
	v_exp_f32_e32 v245, v245
	v_pk_mul_f32 v[130:131], v[140:141], v[136:137]
	v_pk_add_f32 v[244:245], v[244:245], s[98:99]
	v_rcp_f32_e32 v80, v244
	v_rcp_f32_e32 v81, v245
	v_pk_mul_f32 v[244:245], v[134:135], s[100:101]
	v_exp_f32_e32 v244, v244
	v_exp_f32_e32 v245, v245
	v_pk_mul_f32 v[132:133], v[138:139], v[134:135]
	v_pk_add_f32 v[244:245], v[244:245], s[98:99]
	v_rcp_f32_e32 v78, v244
	v_rcp_f32_e32 v79, v245
	v_pk_mul_f32 v[80:81], v[130:131], v[80:81]
	v_pk_mul_f32 v[78:79], v[132:133], v[78:79]
	v_mov_b32_e32 v134, 0
	ds_read_b128 v[142:145], v223 offset:512
	ds_read_b128 v[146:149], v223 offset:1536
	ds_read_b128 v[154:157], v223 offset:2560
	ds_read_b128 v[130:133], v223 offset:3584
	v_mov_b32_e32 v150, 0
	v_mov_b32_e32 v151, 0
	v_mov_b32_e32 v152, 0
	v_mov_b32_e32 v153, 0
	s_and_saveexec_b64 s[52:53], s[0:1]
	v_add_u32_e32 v135, s77, v216
	ds_read_b128 v[150:153], v135 offset:512
	s_or_b64 exec, exec, s[52:53]
	v_fmamk_f32 v136, v204, 0x3a800000, v222
	v_rsq_f32_e32 v160, v136
	s_waitcnt lgkmcnt(0)
	v_pk_fma_f32 v[138:139], v[126:127], v[154:155], v[130:131]
	s_nop 4
	v_fmac_f32_dpp v138, v126, v146 row_shr:1 row_mask:0xf bank_mask:0xf
	v_pk_fma_f32 v[102:103], v[102:103], v[160:161], v[122:123] op_sel_hi:[1,0,1]
	v_fmac_f32_dpp v138, v126, v142 row_shr:2 row_mask:0xf bank_mask:0xf
	v_pk_fma_f32 v[140:141], v[128:129], v[156:157], v[132:133]
	v_fmac_f32_dpp v138, v102, v146 row_shl:15 row_mask:0xf bank_mask:0xf
	v_fmac_f32_dpp v139, v127, v147 row_shr:1 row_mask:0xf bank_mask:0xf
	v_fmac_f32_dpp v138, v102, v142 row_shl:14 row_mask:0xf bank_mask:0xf
	v_fmamk_f32 v135, v206, 0x3a800000, v222
	v_fmac_f32_dpp v139, v127, v143 row_shr:2 row_mask:0xf bank_mask:0xf
	v_rsq_f32_e32 v158, v135
	v_fmac_f32_dpp v139, v103, v147 row_shl:15 row_mask:0xf bank_mask:0xf
	v_fmamk_f32 v135, v207, 0x3a800000, v222
	v_fmac_f32_dpp v139, v103, v143 row_shl:14 row_mask:0xf bank_mask:0xf
	v_fmac_f32_dpp v140, v128, v148 row_shr:1 row_mask:0xf bank_mask:0xf
	v_rsq_f32_e32 v162, v135
	v_fmac_f32_dpp v140, v128, v144 row_shr:2 row_mask:0xf bank_mask:0xf
	v_pk_fma_f32 v[104:105], v[104:105], v[160:161], v[124:125] op_sel_hi:[1,0,1]
	v_pk_fma_f32 v[164:165], v[106:107], v[162:163], v[122:123] op_sel_hi:[1,0,1]
	v_fmac_f32_dpp v141, v129, v149 row_shr:1 row_mask:0xf bank_mask:0xf
	v_fmac_f32_dpp v140, v104, v148 row_shl:15 row_mask:0xf bank_mask:0xf
	v_pk_fma_f32 v[106:107], v[102:103], v[154:155], v[130:131]
	v_fmac_f32_dpp v140, v104, v144 row_shl:14 row_mask:0xf bank_mask:0xf
	v_fmac_f32_dpp v141, v129, v145 row_shr:2 row_mask:0xf bank_mask:0xf
	v_pk_fma_f32 v[136:137], v[108:109], v[162:163], v[124:125] op_sel_hi:[1,0,1]
	v_fmac_f32_dpp v141, v105, v149 row_shl:15 row_mask:0xf bank_mask:0xf
	v_pk_fma_f32 v[108:109], v[104:105], v[156:157], v[132:133]
	v_fmac_f32_dpp v141, v105, v145 row_shl:14 row_mask:0xf bank_mask:0xf
	v_fmac_f32_dpp v106, v102, v146 row_shr:1 row_mask:0xf bank_mask:0xf
	v_pk_fma_f32 v[110:111], v[110:111], v[158:159], v[122:123] op_sel_hi:[1,0,1]
	v_fmac_f32_dpp v106, v102, v142 row_shr:2 row_mask:0xf bank_mask:0xf
	v_fmac_f32_dpp v107, v103, v147 row_shr:1 row_mask:0xf bank_mask:0xf
	v_fmac_f32_dpp v106, v164, v146 row_shl:15 row_mask:0xf bank_mask:0xf
	v_pk_fma_f32 v[112:113], v[112:113], v[158:159], v[124:125] op_sel_hi:[1,0,1]
	v_fmac_f32_dpp v106, v164, v142 row_shl:14 row_mask:0xf bank_mask:0xf
	v_fmac_f32_dpp v107, v103, v143 row_shr:2 row_mask:0xf bank_mask:0xf
	v_pk_fma_f32 v[102:103], v[164:165], v[154:155], v[130:131]
	v_fmac_f32_dpp v107, v165, v147 row_shl:15 row_mask:0xf bank_mask:0xf
	v_pk_fma_f32 v[130:131], v[110:111], v[154:155], v[130:131]
	v_fmac_f32_dpp v107, v165, v143 row_shl:14 row_mask:0xf bank_mask:0xf
	v_fmac_f32_dpp v108, v104, v148 row_shr:1 row_mask:0xf bank_mask:0xf
	v_fmac_f32_dpp v109, v105, v149 row_shr:1 row_mask:0xf bank_mask:0xf
	v_fmac_f32_dpp v108, v104, v144 row_shr:2 row_mask:0xf bank_mask:0xf
	v_fma_f32 v104, v136, v156, v132
	v_fmac_f32_dpp v108, v136, v148 row_shl:15 row_mask:0xf bank_mask:0xf
	v_mov_b32_e32 v135, 0
	v_fmac_f32_dpp v108, v136, v144 row_shl:14 row_mask:0xf bank_mask:0xf
	v_fmac_f32_dpp v109, v105, v145 row_shr:2 row_mask:0xf bank_mask:0xf
	v_fma_f32 v105, v137, v157, v133
	v_fmac_f32_dpp v109, v137, v149 row_shl:15 row_mask:0xf bank_mask:0xf
	v_pk_fma_f32 v[132:133], v[112:113], v[156:157], v[132:133]
	v_fmac_f32_dpp v109, v137, v145 row_shl:14 row_mask:0xf bank_mask:0xf
	v_fmac_f32_dpp v102, v164, v146 row_shr:1 row_mask:0xf bank_mask:0xf
	v_fmac_f32_dpp v103, v165, v147 row_shr:1 row_mask:0xf bank_mask:0xf
	v_fmac_f32_dpp v102, v164, v142 row_shr:2 row_mask:0xf bank_mask:0xf
	v_fmac_f32_dpp v103, v165, v143 row_shr:2 row_mask:0xf bank_mask:0xf
	v_fmac_f32_dpp v102, v110, v146 row_shl:15 row_mask:0xf bank_mask:0xf
	v_fmac_f32_dpp v103, v111, v147 row_shl:15 row_mask:0xf bank_mask:0xf
	v_fmac_f32_dpp v102, v110, v142 row_shl:14 row_mask:0xf bank_mask:0xf
	v_fmac_f32_dpp v103, v111, v143 row_shl:14 row_mask:0xf bank_mask:0xf
	v_fmac_f32_dpp v104, v136, v148 row_shr:1 row_mask:0xf bank_mask:0xf
	v_fmac_f32_dpp v105, v137, v149 row_shr:1 row_mask:0xf bank_mask:0xf
	v_fmac_f32_dpp v104, v136, v144 row_shr:2 row_mask:0xf bank_mask:0xf
	v_mov_b32_e32 v136, 0
	v_fmac_f32_dpp v104, v112, v148 row_shl:15 row_mask:0xf bank_mask:0xf
	v_fmac_f32_dpp v105, v137, v145 row_shr:2 row_mask:0xf bank_mask:0xf
	v_fmac_f32_dpp v104, v112, v144 row_shl:14 row_mask:0xf bank_mask:0xf
	v_mov_b32_e32 v137, 0
	v_fmac_f32_dpp v105, v113, v149 row_shl:15 row_mask:0xf bank_mask:0xf
	v_fmac_f32_dpp v130, v110, v146 row_shr:1 row_mask:0xf bank_mask:0xf
	v_fmac_f32_dpp v105, v113, v145 row_shl:14 row_mask:0xf bank_mask:0xf
	v_fmac_f32_dpp v130, v110, v142 row_shr:2 row_mask:0xf bank_mask:0xf
	v_fmac_f32_dpp v131, v111, v147 row_shr:1 row_mask:0xf bank_mask:0xf
	v_fmac_f32_dpp v130, v150, v146 row_shl:15 row_mask:0xf bank_mask:0xf
	v_fmac_f32_dpp v131, v111, v143 row_shr:2 row_mask:0xf bank_mask:0xf
	v_fmac_f32_dpp v130, v150, v142 row_shl:14 row_mask:0xf bank_mask:0xf
	v_fmac_f32_dpp v131, v151, v147 row_shl:15 row_mask:0xf bank_mask:0xf
	v_fmac_f32_dpp v132, v112, v148 row_shr:1 row_mask:0xf bank_mask:0xf
	v_fmac_f32_dpp v131, v151, v143 row_shl:14 row_mask:0xf bank_mask:0xf
	v_fmac_f32_dpp v132, v112, v144 row_shr:2 row_mask:0xf bank_mask:0xf
	v_fmac_f32_dpp v133, v113, v149 row_shr:1 row_mask:0xf bank_mask:0xf
	v_fmac_f32_dpp v132, v152, v148 row_shl:15 row_mask:0xf bank_mask:0xf
	v_fmac_f32_dpp v133, v113, v145 row_shr:2 row_mask:0xf bank_mask:0xf
	v_fmac_f32_dpp v132, v152, v144 row_shl:14 row_mask:0xf bank_mask:0xf
	v_fmac_f32_dpp v133, v153, v149 row_shl:15 row_mask:0xf bank_mask:0xf
	s_nop 0
	v_fmac_f32_dpp v133, v153, v145 row_shl:14 row_mask:0xf bank_mask:0xf
	ds_read_b128 v[122:125], v223
	ds_read_b128 v[126:129], v223 offset:1024
	ds_read_b128 v[142:145], v223 offset:2048
	ds_read_b128 v[110:113], v223 offset:3072
	s_and_saveexec_b64 s[52:53], s[0:1]
	v_add_u32_e32 v134, 0, v216
	v_add_u32_e32 v134, 0x20000, v134
	ds_read_b128 v[134:137], v134
	s_or_b64 exec, exec, s[52:53]
	v_mov_b32_e32 v159, v158
	v_mov_b32_e32 v161, v160
	v_pk_fma_f32 v[148:149], v[94:95], v[158:159], v[118:119] op_sel_hi:[1,0,1]
	v_pk_fma_f32 v[94:95], v[92:93], v[162:163], v[120:121] op_sel_hi:[1,0,1]
	v_pk_fma_f32 v[92:93], v[86:87], v[160:161], v[118:119] op_sel_hi:[1,0,1]
	s_waitcnt lgkmcnt(0)
	v_pk_fma_f32 v[86:87], v[114:115], v[142:143], v[110:111]
	s_nop 4
	v_fmac_f32_dpp v86, v114, v126 row_shr:1 row_mask:0xf bank_mask:0xf
	v_mov_b32_e32 v163, v162
	v_fmac_f32_dpp v86, v114, v122 row_shr:2 row_mask:0xf bank_mask:0xf
	v_fmac_f32_dpp v87, v115, v127 row_shr:1 row_mask:0xf bank_mask:0xf
	v_fmac_f32_dpp v86, v92, v126 row_shl:15 row_mask:0xf bank_mask:0xf
	v_pk_fma_f32 v[146:147], v[96:97], v[158:159], v[120:121] op_sel_hi:[1,0,1]
	v_fmac_f32_dpp v86, v92, v122 row_shl:14 row_mask:0xf bank_mask:0xf
	v_pk_fma_f32 v[96:97], v[90:91], v[162:163], v[118:119] op_sel_hi:[1,0,1]
	v_fmac_f32_dpp v87, v115, v123 row_shr:2 row_mask:0xf bank_mask:0xf
	v_pk_fma_f32 v[90:91], v[88:89], v[160:161], v[120:121] op_sel_hi:[1,0,1]
	v_fmac_f32_dpp v87, v93, v127 row_shl:15 row_mask:0xf bank_mask:0xf
	v_pk_fma_f32 v[88:89], v[116:117], v[144:145], v[112:113]
	v_fmac_f32_dpp v87, v93, v123 row_shl:14 row_mask:0xf bank_mask:0xf
	v_fmac_f32_dpp v88, v116, v128 row_shr:1 row_mask:0xf bank_mask:0xf
	v_fmac_f32_dpp v89, v117, v129 row_shr:1 row_mask:0xf bank_mask:0xf
	v_fmac_f32_dpp v88, v116, v124 row_shr:2 row_mask:0xf bank_mask:0xf
	v_fmac_f32_dpp v89, v117, v125 row_shr:2 row_mask:0xf bank_mask:0xf
	v_fmac_f32_dpp v88, v90, v128 row_shl:15 row_mask:0xf bank_mask:0xf
	v_fmac_f32_dpp v89, v91, v129 row_shl:15 row_mask:0xf bank_mask:0xf
	v_fmac_f32_dpp v88, v90, v124 row_shl:14 row_mask:0xf bank_mask:0xf
	v_fmac_f32_dpp v89, v91, v125 row_shl:14 row_mask:0xf bank_mask:0xf
	v_pk_mul_f32 v[244:245], v[88:89], s[100:101]
	v_exp_f32_e32 v244, v244
	v_exp_f32_e32 v245, v245
	v_pk_mul_f32 v[88:89], v[140:141], v[88:89]
	v_pk_add_f32 v[244:245], v[244:245], s[98:99]
	v_rcp_f32_e32 v116, v244
	v_rcp_f32_e32 v117, v245
	v_pk_mul_f32 v[244:245], v[86:87], s[100:101]
	v_exp_f32_e32 v244, v244
	v_exp_f32_e32 v245, v245
	v_pk_mul_f32 v[86:87], v[138:139], v[86:87]
	v_pk_add_f32 v[244:245], v[244:245], s[98:99]
	v_rcp_f32_e32 v114, v244
	v_rcp_f32_e32 v115, v245
	v_pk_mul_f32 v[88:89], v[88:89], v[116:117]
	v_pk_mul_f32 v[86:87], v[86:87], v[114:115]
	v_pk_fma_f32 v[114:115], v[92:93], v[142:143], v[110:111]
	s_nop 0
	v_fmac_f32_dpp v114, v92, v126 row_shr:1 row_mask:0xf bank_mask:0xf
	v_fmac_f32_dpp v115, v93, v127 row_shr:1 row_mask:0xf bank_mask:0xf
	v_fmac_f32_dpp v114, v92, v122 row_shr:2 row_mask:0xf bank_mask:0xf
	v_fmac_f32_dpp v115, v93, v123 row_shr:2 row_mask:0xf bank_mask:0xf
	v_fmac_f32_dpp v114, v96, v126 row_shl:15 row_mask:0xf bank_mask:0xf
	v_pk_fma_f32 v[92:93], v[90:91], v[144:145], v[112:113]
	v_fmac_f32_dpp v114, v96, v122 row_shl:14 row_mask:0xf bank_mask:0xf
	v_fmac_f32_dpp v115, v97, v127 row_shl:15 row_mask:0xf bank_mask:0xf
	v_fmac_f32_dpp v92, v90, v128 row_shr:1 row_mask:0xf bank_mask:0xf
	v_fmac_f32_dpp v115, v97, v123 row_shl:14 row_mask:0xf bank_mask:0xf
	v_fmac_f32_dpp v92, v90, v124 row_shr:2 row_mask:0xf bank_mask:0xf
	v_fmac_f32_dpp v93, v91, v129 row_shr:1 row_mask:0xf bank_mask:0xf
	v_fmac_f32_dpp v92, v94, v128 row_shl:15 row_mask:0xf bank_mask:0xf
	v_pk_mul_f32 v[106:107], v[106:107], v[114:115]
	v_fmac_f32_dpp v92, v94, v124 row_shl:14 row_mask:0xf bank_mask:0xf
	v_fmac_f32_dpp v93, v91, v125 row_shr:2 row_mask:0xf bank_mask:0xf
	s_nop 0
	v_fmac_f32_dpp v93, v95, v129 row_shl:15 row_mask:0xf bank_mask:0xf
	s_nop 0
	v_fmac_f32_dpp v93, v95, v125 row_shl:14 row_mask:0xf bank_mask:0xf
	v_pk_mul_f32 v[244:245], v[92:93], s[100:101]
	v_exp_f32_e32 v244, v244
	v_exp_f32_e32 v245, v245
	v_pk_mul_f32 v[92:93], v[108:109], v[92:93]
	v_pk_add_f32 v[244:245], v[244:245], s[98:99]
	v_rcp_f32_e32 v116, v244
	v_rcp_f32_e32 v117, v245
	v_pk_mul_f32 v[244:245], v[114:115], s[100:101]
	v_exp_f32_e32 v244, v244
	v_exp_f32_e32 v245, v245
	v_pk_mul_f32 v[92:93], v[92:93], v[116:117]
	v_pk_add_f32 v[244:245], v[244:245], s[98:99]
	v_rcp_f32_e32 v90, v244
	v_rcp_f32_e32 v91, v245
	s_nop 0
	v_pk_mul_f32 v[90:91], v[106:107], v[90:91]
	v_pk_fma_f32 v[106:107], v[96:97], v[142:143], v[110:111]
	s_nop 0
	v_fmac_f32_dpp v106, v96, v126 row_shr:1 row_mask:0xf bank_mask:0xf
	v_fmac_f32_dpp v107, v97, v127 row_shr:1 row_mask:0xf bank_mask:0xf
	v_fmac_f32_dpp v106, v96, v122 row_shr:2 row_mask:0xf bank_mask:0xf
	v_fma_f32 v96, v94, v144, v112
	v_fmac_f32_dpp v106, v148, v126 row_shl:15 row_mask:0xf bank_mask:0xf
	v_fmac_f32_dpp v107, v97, v123 row_shr:2 row_mask:0xf bank_mask:0xf
	v_fmac_f32_dpp v106, v148, v122 row_shl:14 row_mask:0xf bank_mask:0xf
	v_fma_f32 v97, v95, v145, v113
	v_fmac_f32_dpp v107, v149, v127 row_shl:15 row_mask:0xf bank_mask:0xf
	v_pk_fma_f32 v[112:113], v[146:147], v[144:145], v[112:113]
	v_fmac_f32_dpp v107, v149, v123 row_shl:14 row_mask:0xf bank_mask:0xf
	v_fmac_f32_dpp v96, v94, v128 row_shr:1 row_mask:0xf bank_mask:0xf
	v_fmac_f32_dpp v97, v95, v129 row_shr:1 row_mask:0xf bank_mask:0xf
	v_fmac_f32_dpp v96, v94, v124 row_shr:2 row_mask:0xf bank_mask:0xf
	v_pk_mul_f32 v[102:103], v[102:103], v[106:107]
	v_fmac_f32_dpp v96, v146, v128 row_shl:15 row_mask:0xf bank_mask:0xf
	v_fmac_f32_dpp v97, v95, v125 row_shr:2 row_mask:0xf bank_mask:0xf
	v_fmac_f32_dpp v96, v146, v124 row_shl:14 row_mask:0xf bank_mask:0xf
	v_fmac_f32_dpp v97, v147, v129 row_shl:15 row_mask:0xf bank_mask:0xf
	v_fmac_f32_dpp v112, v146, v128 row_shr:1 row_mask:0xf bank_mask:0xf
	v_fmac_f32_dpp v97, v147, v125 row_shl:14 row_mask:0xf bank_mask:0xf
	v_pk_mul_f32 v[244:245], v[96:97], s[100:101]
	v_exp_f32_e32 v244, v244
	v_exp_f32_e32 v245, v245
	v_pk_mul_f32 v[96:97], v[104:105], v[96:97]
	v_pk_add_f32 v[244:245], v[244:245], s[98:99]
	v_rcp_f32_e32 v108, v244
	v_rcp_f32_e32 v109, v245
	v_pk_mul_f32 v[244:245], v[106:107], s[100:101]
	v_exp_f32_e32 v244, v244
	v_exp_f32_e32 v245, v245
	v_pk_mul_f32 v[96:97], v[96:97], v[108:109]
	v_pk_add_f32 v[244:245], v[244:245], s[98:99]
	v_rcp_f32_e32 v94, v244
	v_rcp_f32_e32 v95, v245
	v_fmac_f32_dpp v112, v146, v124 row_shr:2 row_mask:0xf bank_mask:0xf
	v_pk_mul_f32 v[94:95], v[102:103], v[94:95]
	v_pk_fma_f32 v[102:103], v[148:149], v[142:143], v[110:111]
	v_fmac_f32_dpp v112, v136, v128 row_shl:15 row_mask:0xf bank_mask:0xf
	v_fmac_f32_dpp v102, v148, v126 row_shr:1 row_mask:0xf bank_mask:0xf
	v_fmac_f32_dpp v103, v149, v127 row_shr:1 row_mask:0xf bank_mask:0xf
	v_fmac_f32_dpp v102, v148, v122 row_shr:2 row_mask:0xf bank_mask:0xf
	v_fmac_f32_dpp v103, v149, v123 row_shr:2 row_mask:0xf bank_mask:0xf
	v_fmac_f32_dpp v102, v134, v126 row_shl:15 row_mask:0xf bank_mask:0xf
	v_fmac_f32_dpp v103, v135, v127 row_shl:15 row_mask:0xf bank_mask:0xf
	v_fmac_f32_dpp v102, v134, v122 row_shl:14 row_mask:0xf bank_mask:0xf
	v_mov_b32_e32 v122, 0
	v_fmac_f32_dpp v103, v135, v123 row_shl:14 row_mask:0xf bank_mask:0xf
	v_mov_b32_e32 v123, 0
	v_fmac_f32_dpp v112, v136, v124 row_shl:14 row_mask:0xf bank_mask:0xf
	v_fmac_f32_dpp v113, v147, v129 row_shr:1 row_mask:0xf bank_mask:0xf
	v_mov_b32_e32 v124, 0
	v_fmac_f32_dpp v113, v147, v125 row_shr:2 row_mask:0xf bank_mask:0xf
	s_nop 0
	v_fmac_f32_dpp v113, v137, v129 row_shl:15 row_mask:0xf bank_mask:0xf
	s_nop 0
	v_fmac_f32_dpp v113, v137, v125 row_shl:14 row_mask:0xf bank_mask:0xf
	v_pk_mul_f32 v[244:245], v[112:113], s[100:101]
	v_exp_f32_e32 v244, v244
	v_exp_f32_e32 v245, v245
	v_pk_mul_f32 v[108:109], v[132:133], v[112:113]
	v_pk_add_f32 v[244:245], v[244:245], s[98:99]
	v_rcp_f32_e32 v104, v244
	v_rcp_f32_e32 v105, v245
	v_pk_mul_f32 v[244:245], v[102:103], s[100:101]
	v_exp_f32_e32 v244, v244
	v_exp_f32_e32 v245, v245
	v_pk_mul_f32 v[102:103], v[130:131], v[102:103]
	v_pk_add_f32 v[244:245], v[244:245], s[98:99]
	v_rcp_f32_e32 v106, v244
	v_rcp_f32_e32 v107, v245
	v_pk_mul_f32 v[104:105], v[108:109], v[104:105]
	v_pk_mul_f32 v[102:103], v[102:103], v[106:107]
	ds_read_b128 v[114:117], v223 offset:528
	ds_read_b128 v[118:121], v223 offset:1552
	ds_read_b128 v[126:129], v223 offset:2576
	ds_read_b128 v[106:109], v223 offset:3600
	v_mov_b32_e32 v125, 0
	s_and_saveexec_b64 s[52:53], s[36:37]
	v_add_u32_e32 v110, s77, v217
	ds_read_b128 v[122:125], v110 offset:512
	s_or_b64 exec, exec, s[52:53]
	v_pk_fma_f32 v[76:77], v[76:77], v[196:197], v[56:57] op_sel_hi:[1,0,1]
	v_pk_fma_f32 v[130:131], v[72:73], v[198:199], v[56:57] op_sel_hi:[1,0,1]
	s_waitcnt lgkmcnt(0)
	v_pk_fma_f32 v[110:111], v[98:99], v[126:127], v[106:107]
	s_nop 4
	v_fmac_f32_dpp v110, v98, v118 row_shr:1 row_mask:0xf bank_mask:0xf
	v_pk_fma_f32 v[66:67], v[66:67], v[200:201], v[54:55]
	v_fmac_f32_dpp v110, v98, v114 row_shr:2 row_mask:0xf bank_mask:0xf
	v_pk_fma_f32 v[112:113], v[100:101], v[128:129], v[108:109]
	v_fmac_f32_dpp v110, v66, v118 row_shl:15 row_mask:0xf bank_mask:0xf
	v_fmac_f32_dpp v111, v99, v119 row_shr:1 row_mask:0xf bank_mask:0xf
	v_fmac_f32_dpp v110, v66, v114 row_shl:14 row_mask:0xf bank_mask:0xf
	v_pk_fma_f32 v[132:133], v[70:71], v[198:199], v[54:55]
	v_fmac_f32_dpp v111, v99, v115 row_shr:2 row_mask:0xf bank_mask:0xf
	v_fmac_f32_dpp v112, v100, v120 row_shr:1 row_mask:0xf bank_mask:0xf
	v_fmac_f32_dpp v111, v67, v119 row_shl:15 row_mask:0xf bank_mask:0xf
	v_pk_fma_f32 v[68:69], v[68:69], v[200:201], v[56:57] op_sel_hi:[1,0,1]
	v_fmac_f32_dpp v111, v67, v115 row_shl:14 row_mask:0xf bank_mask:0xf
	v_fmac_f32_dpp v112, v100, v116 row_shr:2 row_mask:0xf bank_mask:0xf
	v_pk_fma_f32 v[70:71], v[66:67], v[126:127], v[106:107]
	v_fmac_f32_dpp v112, v68, v120 row_shl:15 row_mask:0xf bank_mask:0xf
	v_fmac_f32_dpp v113, v101, v121 row_shr:1 row_mask:0xf bank_mask:0xf
	v_fmac_f32_dpp v112, v68, v116 row_shl:14 row_mask:0xf bank_mask:0xf
	v_fmac_f32_dpp v113, v101, v117 row_shr:2 row_mask:0xf bank_mask:0xf
	v_pk_fma_f32 v[72:73], v[68:69], v[128:129], v[108:109]
	v_fmac_f32_dpp v113, v69, v121 row_shl:15 row_mask:0xf bank_mask:0xf
	v_pk_fma_f32 v[74:75], v[74:75], v[196:197], v[54:55]
	v_fmac_f32_dpp v113, v69, v117 row_shl:14 row_mask:0xf bank_mask:0xf
	v_fmac_f32_dpp v70, v66, v118 row_shr:1 row_mask:0xf bank_mask:0xf
	v_fmac_f32_dpp v71, v67, v119 row_shr:1 row_mask:0xf bank_mask:0xf
	v_fmac_f32_dpp v70, v66, v114 row_shr:2 row_mask:0xf bank_mask:0xf
	v_fma_f32 v66, v132, v126, v106
	v_fmac_f32_dpp v70, v132, v118 row_shl:15 row_mask:0xf bank_mask:0xf
	v_fmac_f32_dpp v71, v67, v115 row_shr:2 row_mask:0xf bank_mask:0xf
	v_fmac_f32_dpp v70, v132, v114 row_shl:14 row_mask:0xf bank_mask:0xf
	v_fma_f32 v67, v133, v127, v107
	v_fmac_f32_dpp v71, v133, v119 row_shl:15 row_mask:0xf bank_mask:0xf
	v_pk_fma_f32 v[106:107], v[74:75], v[126:127], v[106:107]
	v_fmac_f32_dpp v71, v133, v115 row_shl:14 row_mask:0xf bank_mask:0xf
	v_fmac_f32_dpp v72, v68, v120 row_shr:1 row_mask:0xf bank_mask:0xf
	v_fmac_f32_dpp v73, v69, v121 row_shr:1 row_mask:0xf bank_mask:0xf
	v_fmac_f32_dpp v72, v68, v116 row_shr:2 row_mask:0xf bank_mask:0xf
	v_fma_f32 v68, v130, v128, v108
	v_fmac_f32_dpp v72, v130, v120 row_shl:15 row_mask:0xf bank_mask:0xf
	v_fmac_f32_dpp v73, v69, v117 row_shr:2 row_mask:0xf bank_mask:0xf
	v_fmac_f32_dpp v72, v130, v116 row_shl:14 row_mask:0xf bank_mask:0xf
	v_fma_f32 v69, v131, v129, v109
	v_fmac_f32_dpp v73, v131, v121 row_shl:15 row_mask:0xf bank_mask:0xf
	v_pk_fma_f32 v[108:109], v[76:77], v[128:129], v[108:109]
	v_fmac_f32_dpp v73, v131, v117 row_shl:14 row_mask:0xf bank_mask:0xf
	v_fmac_f32_dpp v66, v132, v118 row_shr:1 row_mask:0xf bank_mask:0xf
	v_fmac_f32_dpp v67, v133, v119 row_shr:1 row_mask:0xf bank_mask:0xf
	v_fmac_f32_dpp v66, v132, v114 row_shr:2 row_mask:0xf bank_mask:0xf
	v_fmac_f32_dpp v67, v133, v115 row_shr:2 row_mask:0xf bank_mask:0xf
	v_fmac_f32_dpp v66, v74, v118 row_shl:15 row_mask:0xf bank_mask:0xf
	v_fmac_f32_dpp v67, v75, v119 row_shl:15 row_mask:0xf bank_mask:0xf
	v_fmac_f32_dpp v66, v74, v114 row_shl:14 row_mask:0xf bank_mask:0xf
	v_fmac_f32_dpp v67, v75, v115 row_shl:14 row_mask:0xf bank_mask:0xf
	v_fmac_f32_dpp v68, v130, v120 row_shr:1 row_mask:0xf bank_mask:0xf
	v_fmac_f32_dpp v69, v131, v121 row_shr:1 row_mask:0xf bank_mask:0xf
	v_fmac_f32_dpp v68, v130, v116 row_shr:2 row_mask:0xf bank_mask:0xf
	v_fmac_f32_dpp v69, v131, v117 row_shr:2 row_mask:0xf bank_mask:0xf
	v_fmac_f32_dpp v68, v76, v120 row_shl:15 row_mask:0xf bank_mask:0xf
	v_fmac_f32_dpp v69, v77, v121 row_shl:15 row_mask:0xf bank_mask:0xf
	v_fmac_f32_dpp v68, v76, v116 row_shl:14 row_mask:0xf bank_mask:0xf
	v_fmac_f32_dpp v69, v77, v117 row_shl:14 row_mask:0xf bank_mask:0xf
	v_fmac_f32_dpp v106, v74, v118 row_shr:1 row_mask:0xf bank_mask:0xf
	v_fmac_f32_dpp v107, v75, v119 row_shr:1 row_mask:0xf bank_mask:0xf
	v_fmac_f32_dpp v106, v74, v114 row_shr:2 row_mask:0xf bank_mask:0xf
	v_fmac_f32_dpp v107, v75, v115 row_shr:2 row_mask:0xf bank_mask:0xf
	v_fmac_f32_dpp v106, v122, v118 row_shl:15 row_mask:0xf bank_mask:0xf
	v_fmac_f32_dpp v107, v123, v119 row_shl:15 row_mask:0xf bank_mask:0xf
	v_fmac_f32_dpp v106, v122, v114 row_shl:14 row_mask:0xf bank_mask:0xf
	v_fmac_f32_dpp v107, v123, v115 row_shl:14 row_mask:0xf bank_mask:0xf
	v_fmac_f32_dpp v108, v76, v120 row_shr:1 row_mask:0xf bank_mask:0xf
	v_fmac_f32_dpp v109, v77, v121 row_shr:1 row_mask:0xf bank_mask:0xf
	v_fmac_f32_dpp v108, v76, v116 row_shr:2 row_mask:0xf bank_mask:0xf
	v_fmac_f32_dpp v109, v77, v117 row_shr:2 row_mask:0xf bank_mask:0xf
	v_fmac_f32_dpp v108, v124, v120 row_shl:15 row_mask:0xf bank_mask:0xf
	v_fmac_f32_dpp v109, v125, v121 row_shl:15 row_mask:0xf bank_mask:0xf
	v_fmac_f32_dpp v108, v124, v116 row_shl:14 row_mask:0xf bank_mask:0xf
	v_fmac_f32_dpp v109, v125, v117 row_shl:14 row_mask:0xf bank_mask:0xf
	s_and_saveexec_b64 s[52:53], s[38:39]
	s_cbranch_execz .LBB0_1339
	v_or_b32_e32 v74, 4, v202
	v_ashrrev_i32_e32 v75, 31, v74
	v_lshl_add_u64 v[74:75], v[74:75], 2, v[168:169]
	v_add_co_u32_e32 v74, vcc, 0x2000, v74
	s_nop 1
	v_addc_co_u32_e32 v75, vcc, 0, v75, vcc
	global_store_dwordx4 v[74:75], v[106:109], off offset:3072
.LBB0_1339:
	s_or_b64 exec, exec, s[52:53]
	ds_read_b128 v[98:101], v223 offset:16
	ds_read_b128 v[114:117], v223 offset:1040
	ds_read_b128 v[122:125], v223 offset:2064
	ds_read_b128 v[74:77], v223 offset:3088
	v_mov_b32_e32 v118, 0
	v_mov_b32_e32 v119, 0
	v_mov_b32_e32 v120, 0
	v_mov_b32_e32 v121, 0
	s_and_saveexec_b64 s[52:53], s[36:37]
	v_add_u32_e32 v118, 0, v217
	v_add_u32_e32 v118, 0x20000, v118
	ds_read_b128 v[118:121], v118
	s_or_b64 exec, exec, s[52:53]
	v_pk_fma_f32 v[128:129], v[42:43], v[196:197], v[30:31]
	v_pk_fma_f32 v[42:43], v[40:41], v[198:199], v[32:33] op_sel_hi:[1,0,1]
	v_pk_fma_f32 v[40:41], v[34:35], v[200:201], v[30:31]
	s_waitcnt lgkmcnt(0)
	v_pk_fma_f32 v[34:35], v[82:83], v[122:123], v[74:75]
	s_nop 4
	v_fmac_f32_dpp v34, v82, v114 row_shr:1 row_mask:0xf bank_mask:0xf
	v_fmac_f32_dpp v35, v83, v115 row_shr:1 row_mask:0xf bank_mask:0xf
	v_fmac_f32_dpp v34, v82, v98 row_shr:2 row_mask:0xf bank_mask:0xf
	v_pk_fma_f32 v[126:127], v[44:45], v[196:197], v[32:33] op_sel_hi:[1,0,1]
	v_fmac_f32_dpp v34, v40, v114 row_shl:15 row_mask:0xf bank_mask:0xf
	v_pk_fma_f32 v[44:45], v[38:39], v[198:199], v[30:31]
	v_fmac_f32_dpp v34, v40, v98 row_shl:14 row_mask:0xf bank_mask:0xf
	v_fmac_f32_dpp v35, v83, v99 row_shr:2 row_mask:0xf bank_mask:0xf
	v_pk_fma_f32 v[38:39], v[36:37], v[200:201], v[32:33] op_sel_hi:[1,0,1]
	v_fmac_f32_dpp v35, v41, v115 row_shl:15 row_mask:0xf bank_mask:0xf
	v_pk_fma_f32 v[36:37], v[84:85], v[124:125], v[76:77]
	v_fmac_f32_dpp v35, v41, v99 row_shl:14 row_mask:0xf bank_mask:0xf
	v_fmac_f32_dpp v36, v84, v116 row_shr:1 row_mask:0xf bank_mask:0xf
	v_fmac_f32_dpp v37, v85, v117 row_shr:1 row_mask:0xf bank_mask:0xf
	v_fmac_f32_dpp v36, v84, v100 row_shr:2 row_mask:0xf bank_mask:0xf
	v_fmac_f32_dpp v37, v85, v101 row_shr:2 row_mask:0xf bank_mask:0xf
	v_fmac_f32_dpp v36, v38, v116 row_shl:15 row_mask:0xf bank_mask:0xf
	v_fmac_f32_dpp v37, v39, v117 row_shl:15 row_mask:0xf bank_mask:0xf
	v_fmac_f32_dpp v36, v38, v100 row_shl:14 row_mask:0xf bank_mask:0xf
	v_fmac_f32_dpp v37, v39, v101 row_shl:14 row_mask:0xf bank_mask:0xf
	v_pk_mul_f32 v[244:245], v[36:37], s[100:101]
	v_exp_f32_e32 v244, v244
	v_exp_f32_e32 v245, v245
	v_pk_mul_f32 v[36:37], v[112:113], v[36:37]
	v_pk_add_f32 v[244:245], v[244:245], s[98:99]
	v_rcp_f32_e32 v84, v244
	v_rcp_f32_e32 v85, v245
	v_pk_mul_f32 v[244:245], v[34:35], s[100:101]
	v_exp_f32_e32 v244, v244
	v_exp_f32_e32 v245, v245
	v_pk_mul_f32 v[34:35], v[110:111], v[34:35]
	v_pk_add_f32 v[244:245], v[244:245], s[98:99]
	v_rcp_f32_e32 v82, v244
	v_rcp_f32_e32 v83, v245
	v_pk_mul_f32 v[36:37], v[36:37], v[84:85]
	v_pk_mul_f32 v[34:35], v[34:35], v[82:83]
	v_pk_fma_f32 v[82:83], v[40:41], v[122:123], v[74:75]
	s_nop 0
	v_fmac_f32_dpp v82, v40, v114 row_shr:1 row_mask:0xf bank_mask:0xf
	v_fmac_f32_dpp v83, v41, v115 row_shr:1 row_mask:0xf bank_mask:0xf
	v_fmac_f32_dpp v82, v40, v98 row_shr:2 row_mask:0xf bank_mask:0xf
	v_fmac_f32_dpp v83, v41, v99 row_shr:2 row_mask:0xf bank_mask:0xf
	v_fmac_f32_dpp v82, v44, v114 row_shl:15 row_mask:0xf bank_mask:0xf
	v_pk_fma_f32 v[40:41], v[38:39], v[124:125], v[76:77]
	v_fmac_f32_dpp v82, v44, v98 row_shl:14 row_mask:0xf bank_mask:0xf
	v_fmac_f32_dpp v83, v45, v115 row_shl:15 row_mask:0xf bank_mask:0xf
	v_fmac_f32_dpp v40, v38, v116 row_shr:1 row_mask:0xf bank_mask:0xf
	v_fmac_f32_dpp v83, v45, v99 row_shl:14 row_mask:0xf bank_mask:0xf
	v_fmac_f32_dpp v40, v38, v100 row_shr:2 row_mask:0xf bank_mask:0xf
	v_fmac_f32_dpp v41, v39, v117 row_shr:1 row_mask:0xf bank_mask:0xf
	v_fmac_f32_dpp v40, v42, v116 row_shl:15 row_mask:0xf bank_mask:0xf
	v_pk_mul_f32 v[70:71], v[70:71], v[82:83]
	v_fmac_f32_dpp v40, v42, v100 row_shl:14 row_mask:0xf bank_mask:0xf
	v_fmac_f32_dpp v41, v39, v101 row_shr:2 row_mask:0xf bank_mask:0xf
	s_nop 0
	v_fmac_f32_dpp v41, v43, v117 row_shl:15 row_mask:0xf bank_mask:0xf
	s_nop 0
	v_fmac_f32_dpp v41, v43, v101 row_shl:14 row_mask:0xf bank_mask:0xf
	v_pk_mul_f32 v[244:245], v[40:41], s[100:101]
	v_exp_f32_e32 v244, v244
	v_exp_f32_e32 v245, v245
	v_pk_mul_f32 v[40:41], v[72:73], v[40:41]
	v_pk_add_f32 v[244:245], v[244:245], s[98:99]
	v_rcp_f32_e32 v84, v244
	v_rcp_f32_e32 v85, v245
	v_pk_mul_f32 v[244:245], v[82:83], s[100:101]
	v_exp_f32_e32 v244, v244
	v_exp_f32_e32 v245, v245
	v_pk_mul_f32 v[40:41], v[40:41], v[84:85]
	v_pk_add_f32 v[244:245], v[244:245], s[98:99]
	v_rcp_f32_e32 v38, v244
	v_rcp_f32_e32 v39, v245
	s_nop 0
	v_pk_mul_f32 v[38:39], v[70:71], v[38:39]
	v_pk_fma_f32 v[70:71], v[44:45], v[122:123], v[74:75]
	v_pk_fma_f32 v[74:75], v[128:129], v[122:123], v[74:75]
	v_fmac_f32_dpp v70, v44, v114 row_shr:1 row_mask:0xf bank_mask:0xf
	v_fmac_f32_dpp v71, v45, v115 row_shr:1 row_mask:0xf bank_mask:0xf
	v_fmac_f32_dpp v70, v44, v98 row_shr:2 row_mask:0xf bank_mask:0xf
	v_fmac_f32_dpp v71, v45, v99 row_shr:2 row_mask:0xf bank_mask:0xf
	v_fmac_f32_dpp v70, v128, v114 row_shl:15 row_mask:0xf bank_mask:0xf
	v_pk_fma_f32 v[44:45], v[42:43], v[124:125], v[76:77]
	v_fmac_f32_dpp v70, v128, v98 row_shl:14 row_mask:0xf bank_mask:0xf
	v_fmac_f32_dpp v71, v129, v115 row_shl:15 row_mask:0xf bank_mask:0xf
	v_pk_fma_f32 v[76:77], v[126:127], v[124:125], v[76:77]
	v_fmac_f32_dpp v71, v129, v99 row_shl:14 row_mask:0xf bank_mask:0xf
	v_fmac_f32_dpp v44, v42, v116 row_shr:1 row_mask:0xf bank_mask:0xf
	v_fmac_f32_dpp v45, v43, v117 row_shr:1 row_mask:0xf bank_mask:0xf
	v_fmac_f32_dpp v44, v42, v100 row_shr:2 row_mask:0xf bank_mask:0xf
	v_pk_mul_f32 v[66:67], v[66:67], v[70:71]
	v_fmac_f32_dpp v44, v126, v116 row_shl:15 row_mask:0xf bank_mask:0xf
	v_fmac_f32_dpp v45, v43, v101 row_shr:2 row_mask:0xf bank_mask:0xf
	v_fmac_f32_dpp v44, v126, v100 row_shl:14 row_mask:0xf bank_mask:0xf
	v_fmac_f32_dpp v45, v127, v117 row_shl:15 row_mask:0xf bank_mask:0xf
	v_fmac_f32_dpp v74, v128, v114 row_shr:1 row_mask:0xf bank_mask:0xf
	v_fmac_f32_dpp v45, v127, v101 row_shl:14 row_mask:0xf bank_mask:0xf
	v_pk_mul_f32 v[244:245], v[44:45], s[100:101]
	v_exp_f32_e32 v244, v244
	v_exp_f32_e32 v245, v245
	v_pk_mul_f32 v[44:45], v[68:69], v[44:45]
	v_pk_add_f32 v[244:245], v[244:245], s[98:99]
	v_rcp_f32_e32 v72, v244
	v_rcp_f32_e32 v73, v245
	v_pk_mul_f32 v[244:245], v[70:71], s[100:101]
	v_exp_f32_e32 v244, v244
	v_exp_f32_e32 v245, v245
	v_pk_mul_f32 v[44:45], v[44:45], v[72:73]
	v_pk_add_f32 v[244:245], v[244:245], s[98:99]
	v_rcp_f32_e32 v42, v244
	v_rcp_f32_e32 v43, v245
	v_fmac_f32_dpp v74, v128, v98 row_shr:2 row_mask:0xf bank_mask:0xf
	v_pk_mul_f32 v[42:43], v[66:67], v[42:43]
	v_fmac_f32_dpp v74, v118, v114 row_shl:15 row_mask:0xf bank_mask:0xf
	v_fmac_f32_dpp v75, v129, v115 row_shr:1 row_mask:0xf bank_mask:0xf
	v_fmac_f32_dpp v74, v118, v98 row_shl:14 row_mask:0xf bank_mask:0xf
	v_fmac_f32_dpp v75, v129, v99 row_shr:2 row_mask:0xf bank_mask:0xf
	v_fmac_f32_dpp v76, v126, v116 row_shr:1 row_mask:0xf bank_mask:0xf
	v_fmac_f32_dpp v75, v119, v115 row_shl:15 row_mask:0xf bank_mask:0xf
	v_fmac_f32_dpp v76, v126, v100 row_shr:2 row_mask:0xf bank_mask:0xf
	v_fmac_f32_dpp v75, v119, v99 row_shl:14 row_mask:0xf bank_mask:0xf
	v_fmac_f32_dpp v76, v120, v116 row_shl:15 row_mask:0xf bank_mask:0xf
	v_fmac_f32_dpp v77, v127, v117 row_shr:1 row_mask:0xf bank_mask:0xf
	v_fmac_f32_dpp v76, v120, v100 row_shl:14 row_mask:0xf bank_mask:0xf
	v_fmac_f32_dpp v77, v127, v101 row_shr:2 row_mask:0xf bank_mask:0xf
	s_nop 0
	v_fmac_f32_dpp v77, v121, v117 row_shl:15 row_mask:0xf bank_mask:0xf
	s_nop 0
	v_fmac_f32_dpp v77, v121, v101 row_shl:14 row_mask:0xf bank_mask:0xf
	s_and_saveexec_b64 s[52:53], s[38:39]
	s_cbranch_execz .LBB0_1343
	global_store_dwordx4 v[166:167], v[74:77], off offset:16
.LBB0_1343:
	s_or_b64 exec, exec, s[52:53]
	v_pk_mul_f32 v[244:245], v[76:77], s[100:101]
	v_exp_f32_e32 v244, v244
	v_exp_f32_e32 v245, v245
	v_pk_mul_f32 v[70:71], v[108:109], v[76:77]
	v_pk_add_f32 v[244:245], v[244:245], s[98:99]
	v_rcp_f32_e32 v68, v244
	v_rcp_f32_e32 v69, v245
	v_pk_mul_f32 v[244:245], v[74:75], s[100:101]
	v_exp_f32_e32 v244, v244
	v_exp_f32_e32 v245, v245
	v_pk_mul_f32 v[72:73], v[106:107], v[74:75]
	v_pk_add_f32 v[244:245], v[244:245], s[98:99]
	v_rcp_f32_e32 v66, v244
	v_rcp_f32_e32 v67, v245
	v_pk_mul_f32 v[68:69], v[70:71], v[68:69]
	v_pk_mul_f32 v[66:67], v[72:73], v[66:67]
	v_mov_b32_e32 v74, 0
	ds_read_b128 v[98:101], v223 offset:528
	ds_read_b128 v[106:109], v223 offset:1552
	ds_read_b128 v[114:117], v223 offset:2576
	ds_read_b128 v[70:73], v223 offset:3600
	v_mov_b32_e32 v110, 0
	v_mov_b32_e32 v111, 0
	v_mov_b32_e32 v112, 0
	v_mov_b32_e32 v113, 0
	s_and_saveexec_b64 s[52:53], s[0:1]
	v_add_u32_e32 v75, s77, v218
	ds_read_b128 v[110:113], v75 offset:512
	s_or_b64 exec, exec, s[52:53]
	s_waitcnt lgkmcnt(0)
	v_pk_fma_f32 v[82:83], v[58:59], v[114:115], v[70:71]
	s_nop 4
	v_fmac_f32_dpp v82, v58, v106 row_shr:1 row_mask:0xf bank_mask:0xf
	v_pk_fma_f32 v[14:15], v[14:15], v[160:161], v[54:55]
	v_fmac_f32_dpp v82, v58, v98 row_shr:2 row_mask:0xf bank_mask:0xf
	v_pk_fma_f32 v[84:85], v[60:61], v[116:117], v[72:73]
	v_fmac_f32_dpp v82, v14, v106 row_shl:15 row_mask:0xf bank_mask:0xf
	v_fmac_f32_dpp v83, v59, v107 row_shr:1 row_mask:0xf bank_mask:0xf
	v_fmac_f32_dpp v82, v14, v98 row_shl:14 row_mask:0xf bank_mask:0xf
	v_mov_b32_e32 v122, v160
	v_fmac_f32_dpp v83, v59, v99 row_shr:2 row_mask:0xf bank_mask:0xf
	v_mov_b32_e32 v123, v160
	v_fmac_f32_dpp v83, v15, v107 row_shl:15 row_mask:0xf bank_mask:0xf
	v_pk_fma_f32 v[16:17], v[16:17], v[160:161], v[56:57] op_sel_hi:[1,0,1]
	v_fmac_f32_dpp v83, v15, v99 row_shl:14 row_mask:0xf bank_mask:0xf
	v_fmac_f32_dpp v84, v60, v108 row_shr:1 row_mask:0xf bank_mask:0xf
	v_pk_fma_f32 v[124:125], v[18:19], v[162:163], v[54:55]
	v_fmac_f32_dpp v84, v60, v100 row_shr:2 row_mask:0xf bank_mask:0xf
	v_pk_fma_f32 v[18:19], v[14:15], v[114:115], v[70:71]
	v_fmac_f32_dpp v84, v16, v108 row_shl:15 row_mask:0xf bank_mask:0xf
	v_fmac_f32_dpp v85, v61, v109 row_shr:1 row_mask:0xf bank_mask:0xf
	v_fmac_f32_dpp v84, v16, v100 row_shl:14 row_mask:0xf bank_mask:0xf
	v_fmac_f32_dpp v85, v61, v101 row_shr:2 row_mask:0xf bank_mask:0xf
	v_mov_b32_e32 v120, v162
	v_fmac_f32_dpp v85, v17, v109 row_shl:15 row_mask:0xf bank_mask:0xf
	v_mov_b32_e32 v121, v162
	v_fmac_f32_dpp v85, v17, v101 row_shl:14 row_mask:0xf bank_mask:0xf
	v_pk_fma_f32 v[76:77], v[20:21], v[162:163], v[56:57] op_sel_hi:[1,0,1]
	v_fmac_f32_dpp v18, v14, v106 row_shr:1 row_mask:0xf bank_mask:0xf
	v_pk_fma_f32 v[20:21], v[16:17], v[116:117], v[72:73]
	v_fmac_f32_dpp v18, v14, v98 row_shr:2 row_mask:0xf bank_mask:0xf
	v_fmac_f32_dpp v19, v15, v107 row_shr:1 row_mask:0xf bank_mask:0xf
	v_fmac_f32_dpp v18, v124, v106 row_shl:15 row_mask:0xf bank_mask:0xf
	v_pk_fma_f32 v[22:23], v[22:23], v[158:159], v[54:55]
	v_fmac_f32_dpp v18, v124, v98 row_shl:14 row_mask:0xf bank_mask:0xf
	v_fmac_f32_dpp v19, v15, v99 row_shr:2 row_mask:0xf bank_mask:0xf
	v_pk_fma_f32 v[14:15], v[124:125], v[114:115], v[70:71]
	v_fmac_f32_dpp v19, v125, v107 row_shl:15 row_mask:0xf bank_mask:0xf
	v_mov_b32_e32 v118, v158
	v_fmac_f32_dpp v19, v125, v99 row_shl:14 row_mask:0xf bank_mask:0xf
	v_fmac_f32_dpp v20, v16, v108 row_shr:1 row_mask:0xf bank_mask:0xf
	v_mov_b32_e32 v119, v158
	v_fmac_f32_dpp v20, v16, v100 row_shr:2 row_mask:0xf bank_mask:0xf
	v_pk_fma_f32 v[24:25], v[24:25], v[158:159], v[56:57] op_sel_hi:[1,0,1]
	v_fmac_f32_dpp v20, v76, v108 row_shl:15 row_mask:0xf bank_mask:0xf
	v_fmac_f32_dpp v21, v17, v109 row_shr:1 row_mask:0xf bank_mask:0xf
	v_fmac_f32_dpp v20, v76, v100 row_shl:14 row_mask:0xf bank_mask:0xf
	v_pk_fma_f32 v[70:71], v[22:23], v[114:115], v[70:71]
	v_fmac_f32_dpp v21, v17, v101 row_shr:2 row_mask:0xf bank_mask:0xf
	v_pk_fma_f32 v[16:17], v[76:77], v[116:117], v[72:73]
	v_fmac_f32_dpp v21, v77, v109 row_shl:15 row_mask:0xf bank_mask:0xf
	v_pk_fma_f32 v[72:73], v[24:25], v[116:117], v[72:73]
	v_fmac_f32_dpp v21, v77, v101 row_shl:14 row_mask:0xf bank_mask:0xf
	v_fmac_f32_dpp v14, v124, v106 row_shr:1 row_mask:0xf bank_mask:0xf
	v_mov_b32_e32 v75, 0
	v_fmac_f32_dpp v14, v124, v98 row_shr:2 row_mask:0xf bank_mask:0xf
	v_fmac_f32_dpp v15, v125, v107 row_shr:1 row_mask:0xf bank_mask:0xf
	v_fmac_f32_dpp v14, v22, v106 row_shl:15 row_mask:0xf bank_mask:0xf
	v_fmac_f32_dpp v15, v125, v99 row_shr:2 row_mask:0xf bank_mask:0xf
	v_fmac_f32_dpp v14, v22, v98 row_shl:14 row_mask:0xf bank_mask:0xf
	v_fmac_f32_dpp v15, v23, v107 row_shl:15 row_mask:0xf bank_mask:0xf
	v_fmac_f32_dpp v16, v76, v108 row_shr:1 row_mask:0xf bank_mask:0xf
	v_fmac_f32_dpp v15, v23, v99 row_shl:14 row_mask:0xf bank_mask:0xf
	v_fmac_f32_dpp v16, v76, v100 row_shr:2 row_mask:0xf bank_mask:0xf
	v_mov_b32_e32 v76, 0
	v_fmac_f32_dpp v16, v24, v108 row_shl:15 row_mask:0xf bank_mask:0xf
	v_fmac_f32_dpp v17, v77, v109 row_shr:1 row_mask:0xf bank_mask:0xf
	v_fmac_f32_dpp v16, v24, v100 row_shl:14 row_mask:0xf bank_mask:0xf
	v_fmac_f32_dpp v17, v77, v101 row_shr:2 row_mask:0xf bank_mask:0xf
	v_mov_b32_e32 v77, 0
	v_fmac_f32_dpp v17, v25, v109 row_shl:15 row_mask:0xf bank_mask:0xf
	v_fmac_f32_dpp v70, v22, v106 row_shr:1 row_mask:0xf bank_mask:0xf
	v_fmac_f32_dpp v17, v25, v101 row_shl:14 row_mask:0xf bank_mask:0xf
	v_fmac_f32_dpp v70, v22, v98 row_shr:2 row_mask:0xf bank_mask:0xf
	v_fmac_f32_dpp v71, v23, v107 row_shr:1 row_mask:0xf bank_mask:0xf
	v_fmac_f32_dpp v70, v110, v106 row_shl:15 row_mask:0xf bank_mask:0xf
	v_fmac_f32_dpp v71, v23, v99 row_shr:2 row_mask:0xf bank_mask:0xf
	v_fmac_f32_dpp v70, v110, v98 row_shl:14 row_mask:0xf bank_mask:0xf
	v_fmac_f32_dpp v71, v111, v107 row_shl:15 row_mask:0xf bank_mask:0xf
	v_fmac_f32_dpp v72, v24, v108 row_shr:1 row_mask:0xf bank_mask:0xf
	v_fmac_f32_dpp v71, v111, v99 row_shl:14 row_mask:0xf bank_mask:0xf
	v_fmac_f32_dpp v72, v24, v100 row_shr:2 row_mask:0xf bank_mask:0xf
	v_fmac_f32_dpp v73, v25, v109 row_shr:1 row_mask:0xf bank_mask:0xf
	v_fmac_f32_dpp v72, v112, v108 row_shl:15 row_mask:0xf bank_mask:0xf
	v_fmac_f32_dpp v73, v25, v101 row_shr:2 row_mask:0xf bank_mask:0xf
	v_fmac_f32_dpp v72, v112, v100 row_shl:14 row_mask:0xf bank_mask:0xf
	v_fmac_f32_dpp v73, v113, v109 row_shl:15 row_mask:0xf bank_mask:0xf
	s_nop 0
	v_fmac_f32_dpp v73, v113, v101 row_shl:14 row_mask:0xf bank_mask:0xf
	ds_read_b128 v[54:57], v223 offset:16
	ds_read_b128 v[58:61], v223 offset:1040
	ds_read_b128 v[98:101], v223 offset:2064
	ds_read_b128 v[22:25], v223 offset:3088
	s_and_saveexec_b64 s[52:53], s[0:1]
	v_add_u32_e32 v74, 0, v218
	v_add_u32_e32 v74, 0x20000, v74
	ds_read_b128 v[74:77], v74
	s_or_b64 exec, exec, s[52:53]
	v_pk_fma_f32 v[106:107], v[8:9], v[162:163], v[32:33] op_sel_hi:[1,0,1]
	v_pk_fma_f32 v[8:9], v[2:3], v[160:161], v[30:31]
	s_waitcnt lgkmcnt(0)
	v_pk_fma_f32 v[2:3], v[26:27], v[98:99], v[22:23]
	s_nop 4
	v_fmac_f32_dpp v2, v26, v58 row_shr:1 row_mask:0xf bank_mask:0xf
	v_pk_fma_f32 v[108:109], v[6:7], v[162:163], v[30:31]
	v_fmac_f32_dpp v2, v26, v54 row_shr:2 row_mask:0xf bank_mask:0xf
	v_pk_fma_f32 v[6:7], v[4:5], v[160:161], v[32:33] op_sel_hi:[1,0,1]
	v_fmac_f32_dpp v2, v8, v58 row_shl:15 row_mask:0xf bank_mask:0xf
	v_fmac_f32_dpp v3, v27, v59 row_shr:1 row_mask:0xf bank_mask:0xf
	v_fmac_f32_dpp v2, v8, v54 row_shl:14 row_mask:0xf bank_mask:0xf
	v_pk_fma_f32 v[4:5], v[28:29], v[100:101], v[24:25]
	v_fmac_f32_dpp v3, v27, v55 row_shr:2 row_mask:0xf bank_mask:0xf
	v_fmac_f32_dpp v4, v28, v60 row_shr:1 row_mask:0xf bank_mask:0xf
	v_fmac_f32_dpp v3, v9, v59 row_shl:15 row_mask:0xf bank_mask:0xf
	v_fmac_f32_dpp v4, v28, v56 row_shr:2 row_mask:0xf bank_mask:0xf
	v_fmac_f32_dpp v3, v9, v55 row_shl:14 row_mask:0xf bank_mask:0xf
	v_fmac_f32_dpp v4, v6, v60 row_shl:15 row_mask:0xf bank_mask:0xf
	v_fmac_f32_dpp v5, v29, v61 row_shr:1 row_mask:0xf bank_mask:0xf
	v_fmac_f32_dpp v4, v6, v56 row_shl:14 row_mask:0xf bank_mask:0xf
	v_fmac_f32_dpp v5, v29, v57 row_shr:2 row_mask:0xf bank_mask:0xf
	v_pk_fma_f32 v[10:11], v[10:11], v[158:159], v[30:31]
	v_fmac_f32_dpp v5, v7, v61 row_shl:15 row_mask:0xf bank_mask:0xf
	v_pk_fma_f32 v[12:13], v[12:13], v[158:159], v[32:33] op_sel_hi:[1,0,1]
	v_fmac_f32_dpp v5, v7, v57 row_shl:14 row_mask:0xf bank_mask:0xf
	v_pk_mul_f32 v[244:245], v[4:5], s[100:101]
	v_exp_f32_e32 v244, v244
	v_exp_f32_e32 v245, v245
	v_pk_mul_f32 v[4:5], v[84:85], v[4:5]
	v_pk_add_f32 v[244:245], v[244:245], s[98:99]
	v_rcp_f32_e32 v28, v244
	v_rcp_f32_e32 v29, v245
	v_pk_mul_f32 v[244:245], v[2:3], s[100:101]
	v_exp_f32_e32 v244, v244
	v_exp_f32_e32 v245, v245
	v_pk_mul_f32 v[2:3], v[82:83], v[2:3]
	v_pk_add_f32 v[244:245], v[244:245], s[98:99]
	v_rcp_f32_e32 v26, v244
	v_rcp_f32_e32 v27, v245
	v_pk_mul_f32 v[4:5], v[4:5], v[28:29]
	v_pk_mul_f32 v[2:3], v[2:3], v[26:27]
	v_pk_fma_f32 v[26:27], v[8:9], v[98:99], v[22:23]
	s_nop 0
	v_fmac_f32_dpp v26, v8, v58 row_shr:1 row_mask:0xf bank_mask:0xf
	v_fmac_f32_dpp v27, v9, v59 row_shr:1 row_mask:0xf bank_mask:0xf
	v_fmac_f32_dpp v26, v8, v54 row_shr:2 row_mask:0xf bank_mask:0xf
	v_fmac_f32_dpp v27, v9, v55 row_shr:2 row_mask:0xf bank_mask:0xf
	v_fmac_f32_dpp v26, v108, v58 row_shl:15 row_mask:0xf bank_mask:0xf
	v_pk_fma_f32 v[8:9], v[6:7], v[100:101], v[24:25]
	v_fmac_f32_dpp v26, v108, v54 row_shl:14 row_mask:0xf bank_mask:0xf
	v_fmac_f32_dpp v27, v109, v59 row_shl:15 row_mask:0xf bank_mask:0xf
	s_ashr_i32 s51, s50, 31
	v_fmac_f32_dpp v27, v109, v55 row_shl:14 row_mask:0xf bank_mask:0xf
	v_fmac_f32_dpp v8, v6, v60 row_shr:1 row_mask:0xf bank_mask:0xf
	s_andn2_b64 vcc, exec, s[4:5]
	v_fmac_f32_dpp v8, v6, v56 row_shr:2 row_mask:0xf bank_mask:0xf
	v_fmac_f32_dpp v9, v7, v61 row_shr:1 row_mask:0xf bank_mask:0xf
	v_fmac_f32_dpp v8, v106, v60 row_shl:15 row_mask:0xf bank_mask:0xf
	v_pk_mul_f32 v[18:19], v[18:19], v[26:27]
	v_fmac_f32_dpp v8, v106, v56 row_shl:14 row_mask:0xf bank_mask:0xf
	v_fmac_f32_dpp v9, v7, v57 row_shr:2 row_mask:0xf bank_mask:0xf
	s_nop 0
	v_fmac_f32_dpp v9, v107, v61 row_shl:15 row_mask:0xf bank_mask:0xf
	s_nop 0
	v_fmac_f32_dpp v9, v107, v57 row_shl:14 row_mask:0xf bank_mask:0xf
	v_pk_mul_f32 v[244:245], v[8:9], s[100:101]
	v_exp_f32_e32 v244, v244
	v_exp_f32_e32 v245, v245
	v_pk_mul_f32 v[8:9], v[20:21], v[8:9]
	v_pk_add_f32 v[244:245], v[244:245], s[98:99]
	v_rcp_f32_e32 v28, v244
	v_rcp_f32_e32 v29, v245
	v_pk_mul_f32 v[244:245], v[26:27], s[100:101]
	v_exp_f32_e32 v244, v244
	v_exp_f32_e32 v245, v245
	v_pk_fma_f32 v[20:21], v[106:107], v[100:101], v[24:25]
	v_pk_add_f32 v[244:245], v[244:245], s[98:99]
	v_rcp_f32_e32 v6, v244
	v_rcp_f32_e32 v7, v245
	v_pk_mul_f32 v[8:9], v[8:9], v[28:29]
	v_pk_mul_f32 v[6:7], v[18:19], v[6:7]
	v_pk_fma_f32 v[18:19], v[108:109], v[98:99], v[22:23]
	v_pk_fma_f32 v[24:25], v[12:13], v[100:101], v[24:25]
	v_fmac_f32_dpp v18, v108, v58 row_shr:1 row_mask:0xf bank_mask:0xf
	v_fmac_f32_dpp v19, v109, v59 row_shr:1 row_mask:0xf bank_mask:0xf
	v_fmac_f32_dpp v18, v108, v54 row_shr:2 row_mask:0xf bank_mask:0xf
	v_fmac_f32_dpp v19, v109, v55 row_shr:2 row_mask:0xf bank_mask:0xf
	v_fmac_f32_dpp v18, v10, v58 row_shl:15 row_mask:0xf bank_mask:0xf
	v_fmac_f32_dpp v19, v11, v59 row_shl:15 row_mask:0xf bank_mask:0xf
	v_fmac_f32_dpp v18, v10, v54 row_shl:14 row_mask:0xf bank_mask:0xf
	v_fmac_f32_dpp v19, v11, v55 row_shl:14 row_mask:0xf bank_mask:0xf
	v_fmac_f32_dpp v20, v106, v60 row_shr:1 row_mask:0xf bank_mask:0xf
	s_mov_b64 s[4:5], -1
	v_fmac_f32_dpp v20, v106, v56 row_shr:2 row_mask:0xf bank_mask:0xf
	v_fmac_f32_dpp v21, v107, v61 row_shr:1 row_mask:0xf bank_mask:0xf
	v_fmac_f32_dpp v20, v12, v60 row_shl:15 row_mask:0xf bank_mask:0xf
	v_fmac_f32_dpp v21, v107, v57 row_shr:2 row_mask:0xf bank_mask:0xf
	v_fmac_f32_dpp v20, v12, v56 row_shl:14 row_mask:0xf bank_mask:0xf
	v_fmac_f32_dpp v21, v13, v61 row_shl:15 row_mask:0xf bank_mask:0xf
	v_pk_mul_f32 v[14:15], v[14:15], v[18:19]
	v_fmac_f32_dpp v21, v13, v57 row_shl:14 row_mask:0xf bank_mask:0xf
	v_pk_mul_f32 v[244:245], v[20:21], s[100:101]
	v_exp_f32_e32 v244, v244
	v_exp_f32_e32 v245, v245
	v_pk_mul_f32 v[16:17], v[16:17], v[20:21]
	v_pk_add_f32 v[244:245], v[244:245], s[98:99]
	v_rcp_f32_e32 v28, v244
	v_rcp_f32_e32 v29, v245
	v_pk_mul_f32 v[244:245], v[18:19], s[100:101]
	v_exp_f32_e32 v244, v244
	v_exp_f32_e32 v245, v245
	v_pk_mul_f32 v[16:17], v[16:17], v[28:29]
	v_pk_add_f32 v[244:245], v[244:245], s[98:99]
	v_rcp_f32_e32 v26, v244
	v_rcp_f32_e32 v27, v245
	v_pk_fma_f32 v[18:19], v[10:11], v[98:99], v[22:23]
	v_pk_mul_f32 v[14:15], v[14:15], v[26:27]
	v_fmac_f32_dpp v18, v10, v58 row_shr:1 row_mask:0xf bank_mask:0xf
	v_lshl_add_u32 v26, s30, 8, v173
	v_fmac_f32_dpp v18, v10, v54 row_shr:2 row_mask:0xf bank_mask:0xf
	v_mov_b64_e32 v[22:23], s[66:67]
	v_fmac_f32_dpp v18, v74, v58 row_shl:15 row_mask:0xf bank_mask:0xf
	v_fmac_f32_dpp v19, v11, v59 row_shr:1 row_mask:0xf bank_mask:0xf
	v_fmac_f32_dpp v18, v74, v54 row_shl:14 row_mask:0xf bank_mask:0xf
	v_fmac_f32_dpp v19, v11, v55 row_shr:2 row_mask:0xf bank_mask:0xf
	v_fmac_f32_dpp v24, v12, v60 row_shr:1 row_mask:0xf bank_mask:0xf
	v_fmac_f32_dpp v19, v75, v59 row_shl:15 row_mask:0xf bank_mask:0xf
	v_fmac_f32_dpp v24, v12, v56 row_shr:2 row_mask:0xf bank_mask:0xf
	v_fmac_f32_dpp v19, v75, v55 row_shl:14 row_mask:0xf bank_mask:0xf
	v_fmac_f32_dpp v24, v76, v60 row_shl:15 row_mask:0xf bank_mask:0xf
	v_fmac_f32_dpp v25, v13, v61 row_shr:1 row_mask:0xf bank_mask:0xf
	v_fmac_f32_dpp v24, v76, v56 row_shl:14 row_mask:0xf bank_mask:0xf
	v_fmac_f32_dpp v25, v13, v57 row_shr:2 row_mask:0xf bank_mask:0xf
	s_nop 0
	v_fmac_f32_dpp v25, v77, v61 row_shl:15 row_mask:0xf bank_mask:0xf
	s_nop 0
	v_fmac_f32_dpp v25, v77, v57 row_shl:14 row_mask:0xf bank_mask:0xf
	v_pk_mul_f32 v[244:245], v[24:25], s[100:101]
	v_exp_f32_e32 v244, v244
	v_exp_f32_e32 v245, v245
	v_pk_mul_f32 v[20:21], v[72:73], v[24:25]
	v_pk_add_f32 v[244:245], v[244:245], s[98:99]
	v_rcp_f32_e32 v12, v244
	v_rcp_f32_e32 v13, v245
	v_pk_mul_f32 v[244:245], v[18:19], s[100:101]
	v_exp_f32_e32 v244, v244
	v_exp_f32_e32 v245, v245
	s_nop 0
	v_pk_add_f32 v[244:245], v[244:245], s[98:99]
	v_rcp_f32_e32 v10, v244
	v_rcp_f32_e32 v11, v245
	v_mad_i64_i32 v[24:25], s[30:31], v26, s81, v[22:23]
	s_lshl_b64 s[30:31], s[50:51], 1
	v_pk_mul_f32 v[18:19], v[70:71], v[18:19]
	v_lshl_add_u64 v[24:25], v[24:25], 0, s[30:31]
	v_pk_mul_f32 v[12:13], v[20:21], v[12:13]
	v_pk_mul_f32 v[10:11], v[18:19], v[10:11]
	v_lshl_add_u64 v[24:25], v[24:25], 0, v[184:185]
	v_cvt_pk_bf16_f32 v18, v78, v79
	v_cvt_pk_bf16_f32 v19, v80, v81
	v_cvt_pk_bf16_f32 v20, v66, v67
	v_cvt_pk_bf16_f32 v21, v68, v69
	global_store_dwordx4 v[24:25], v[18:21], off
	v_or_b32_e32 v24, 16, v26
	v_mad_i64_i32 v[24:25], s[50:51], v24, s81, v[22:23]
	v_lshl_add_u64 v[24:25], v[24:25], 0, s[30:31]
	v_lshl_add_u64 v[24:25], v[24:25], 0, v[184:185]
	v_cvt_pk_bf16_f32 v18, v62, v63
	v_cvt_pk_bf16_f32 v19, v64, v65
	v_cvt_pk_bf16_f32 v20, v42, v43
	v_cvt_pk_bf16_f32 v21, v44, v45
	global_store_dwordx4 v[24:25], v[18:21], off
	v_or_b32_e32 v24, 32, v26
	v_mad_i64_i32 v[24:25], s[50:51], v24, s81, v[22:23]
	v_lshl_add_u64 v[24:25], v[24:25], 0, s[30:31]
	v_lshl_add_u64 v[24:25], v[24:25], 0, v[184:185]
	v_cvt_pk_bf16_f32 v18, v50, v51
	v_cvt_pk_bf16_f32 v19, v52, v53
	v_cvt_pk_bf16_f32 v20, v38, v39
	v_cvt_pk_bf16_f32 v21, v40, v41
	global_store_dwordx4 v[24:25], v[18:21], off
	v_or_b32_e32 v24, 48, v26
	v_mad_i64_i32 v[24:25], s[50:51], v24, s81, v[22:23]
	v_lshl_add_u64 v[24:25], v[24:25], 0, s[30:31]
	v_lshl_add_u64 v[24:25], v[24:25], 0, v[184:185]
	v_cvt_pk_bf16_f32 v18, v46, v47
	v_cvt_pk_bf16_f32 v19, v48, v49
	v_cvt_pk_bf16_f32 v20, v34, v35
	v_cvt_pk_bf16_f32 v21, v36, v37
	global_store_dwordx4 v[24:25], v[18:21], off
	v_add_u32_e32 v24, 0x80, v26
	s_nop 0
	v_cvt_pk_bf16_f32 v18, v102, v103
	v_cvt_pk_bf16_f32 v19, v104, v105
	v_cvt_pk_bf16_f32 v20, v10, v11
	v_mad_i64_i32 v[10:11], s[50:51], v24, s81, v[22:23]
	v_lshl_add_u64 v[10:11], v[10:11], 0, s[30:31]
	v_lshl_add_u64 v[10:11], v[10:11], 0, v[184:185]
	v_cvt_pk_bf16_f32 v21, v12, v13
	global_store_dwordx4 v[10:11], v[18:21], off
	v_cvt_pk_bf16_f32 v10, v94, v95
	v_cvt_pk_bf16_f32 v11, v96, v97
	v_cvt_pk_bf16_f32 v12, v14, v15
	v_add_u32_e32 v14, 0x90, v26
	v_mad_i64_i32 v[14:15], s[50:51], v14, s81, v[22:23]
	v_lshl_add_u64 v[14:15], v[14:15], 0, s[30:31]
	v_lshl_add_u64 v[14:15], v[14:15], 0, v[184:185]
	v_cvt_pk_bf16_f32 v13, v16, v17
	global_store_dwordx4 v[14:15], v[10:13], off
	s_nop 1
	v_cvt_pk_bf16_f32 v10, v90, v91
	v_cvt_pk_bf16_f32 v11, v92, v93
	v_cvt_pk_bf16_f32 v12, v6, v7
	v_add_u32_e32 v6, 0xa0, v26
	v_mad_i64_i32 v[6:7], s[50:51], v6, s81, v[22:23]
	v_lshl_add_u64 v[6:7], v[6:7], 0, s[30:31]
	v_lshl_add_u64 v[6:7], v[6:7], 0, v[184:185]
	v_cvt_pk_bf16_f32 v13, v8, v9
	global_store_dwordx4 v[6:7], v[10:13], off
	v_cvt_pk_bf16_f32 v6, v86, v87
	v_cvt_pk_bf16_f32 v7, v88, v89
	v_cvt_pk_bf16_f32 v8, v2, v3
	v_add_u32_e32 v2, 0xb0, v26
	v_mad_i64_i32 v[2:3], s[50:51], v2, s81, v[22:23]
	v_lshl_add_u64 v[2:3], v[2:3], 0, s[30:31]
	v_lshl_add_u64 v[2:3], v[2:3], 0, v[184:185]
	v_cvt_pk_bf16_f32 v9, v4, v5
	global_store_dwordx4 v[2:3], v[6:9], off
	s_cbranch_vccnz .LBB0_1313
	s_andn2_b64 vcc, exec, s[20:21]
	s_mov_b32 s43, s44
	s_mov_b64 s[30:31], s[16:17]
	s_mov_b64 s[4:5], s[40:41]
	s_cbranch_vccnz .LBB0_1350
	s_ashr_i32 s4, s44, 5
	s_mul_hi_i32 s5, s4, 0x5800
	s_mulk_i32 s4, 0x5800
	s_add_u32 s30, s3, s4
	s_addc_u32 s31, s6, s5
	s_mov_b32 s43, s42
	s_mov_b64 s[4:5], s[14:15]
